# S5-out epilogue: packed f32 ops as plain per-element ops (on top of v66)
# baseline (speedup 1.0000x reference)
; #define GAS __attribute__((address_space(1)))
; #define LAS __attribute__((address_space(3)))
; __device__ __forceinline__ void ph_s5_out(Frame& F) {
;     ...
;         for (int s0 = 0; s0 < 64; s0 += 16) {
;             bf16x8_t bq[16];
; #pragma unroll
;             for (int e = 0; e < 16; ++e) bq[e] = *(const GAS bf16x8_t*)(ub + 512 * (s0 + e));
; #pragma unroll
;             for (int e = 0; e < 16; ++e) { const int sI = s0 + e; const bf16x8_t b = bq[e];
; #pragma unroll
;             for (int i = 0; i < 4; ++i) { const bf16x8_t a = *(const LAS bf16x8_t*)(tl + (16 * i - sI) * 16 * TP_PITCH); acc[i] = __builtin_amdgcn_mfma_f32_32x32x16_bf16(a, b, acc[i], 0, 0, 0); }
;             }
;         }
.LBB0_972:
	v_add_co_u32_e32 v210, vcc, 0x2000, v82
	s_nop 1
	v_addc_co_u32_e32 v211, vcc, 0, v83, vcc
	v_add_co_u32_e32 v212, vcc, 0x4000, v82
	s_nop 1
	v_addc_co_u32_e32 v213, vcc, 0, v83, vcc
	ds_read_b128 v[84:87], v68 offset:11520
	ds_read_b128 v[96:99], v68 offset:12288
	s_waitcnt vmcnt(15) lgkmcnt(1)
	v_mfma_f32_32x32x16_bf16 v[50:65], v[84:87], v[142:145], v[50:65]
	ds_read_b128 v[84:87], v68 offset:23808
	ds_read_b128 v[108:111], v68 offset:24576
	s_waitcnt lgkmcnt(1)
	v_mfma_f32_32x32x16_bf16 v[34:49], v[84:87], v[142:145], v[34:49]
	ds_read_b128 v[84:87], v68 offset:36096
	ds_read_b128 v[112:115], v68 offset:36864
	s_waitcnt lgkmcnt(1)
	v_mfma_f32_32x32x16_bf16 v[18:33], v[84:87], v[142:145], v[18:33]
	ds_read_b128 v[84:87], v68 offset:48384
	ds_read_b128 v[116:119], v68
	s_waitcnt lgkmcnt(1)
	v_mfma_f32_32x32x16_bf16 v[2:17], v[84:87], v[142:145], v[2:17]
	global_load_dwordx4 v[142:145], v[82:83], off offset:1024
	ds_read_b128 v[84:87], v68 offset:10752
	ds_read_b128 v[100:103], v68 offset:9984
	s_waitcnt vmcnt(15) lgkmcnt(1)
	v_mfma_f32_32x32x16_bf16 v[50:65], v[84:87], v[146:149], v[50:65]
	ds_read_b128 v[84:87], v68 offset:23040
	ds_read_b128 v[120:123], v68 offset:22272
	s_waitcnt lgkmcnt(1)
	v_mfma_f32_32x32x16_bf16 v[34:49], v[84:87], v[146:149], v[34:49]
	ds_read_b128 v[84:87], v68 offset:35328
	ds_read_b128 v[124:127], v68 offset:34560
	ds_read_b128 v[128:131], v68 offset:46848
	s_waitcnt lgkmcnt(2)
	v_mfma_f32_32x32x16_bf16 v[18:33], v[84:87], v[146:149], v[18:33]
	ds_read_b128 v[84:87], v68 offset:47616
	s_waitcnt lgkmcnt(0)
	v_mfma_f32_32x32x16_bf16 v[2:17], v[84:87], v[146:149], v[2:17]
	global_load_dwordx4 v[146:149], v[82:83], off offset:2048
	s_waitcnt vmcnt(15)
	v_mfma_f32_32x32x16_bf16 v[50:65], v[100:103], v[150:153], v[50:65]
	v_mfma_f32_32x32x16_bf16 v[34:49], v[120:123], v[150:153], v[34:49]
	ds_read_b128 v[100:103], v68 offset:9216
	ds_read_b128 v[120:123], v68 offset:8448
	v_mfma_f32_32x32x16_bf16 v[18:33], v[124:127], v[150:153], v[18:33]
	v_mfma_f32_32x32x16_bf16 v[2:17], v[128:131], v[150:153], v[2:17]
	global_load_dwordx4 v[150:153], v[82:83], off offset:3072
	s_waitcnt vmcnt(15) lgkmcnt(1)
	v_mfma_f32_32x32x16_bf16 v[50:65], v[100:103], v[154:157], v[50:65]
	ds_read_b128 v[100:103], v68 offset:21504
	ds_read_b128 v[128:131], v68 offset:20736
	s_waitcnt lgkmcnt(1)
	v_mfma_f32_32x32x16_bf16 v[34:49], v[100:103], v[154:157], v[34:49]
	ds_read_b128 v[100:103], v68 offset:33792
	ds_read_b128 v[132:135], v68 offset:33024
	s_waitcnt lgkmcnt(1)
	v_mfma_f32_32x32x16_bf16 v[18:33], v[100:103], v[154:157], v[18:33]
	ds_read_b128 v[100:103], v68 offset:46080
	ds_read_b128 v[136:139], v68 offset:45312
	s_waitcnt lgkmcnt(1)
	v_mfma_f32_32x32x16_bf16 v[2:17], v[100:103], v[154:157], v[2:17]
	global_load_dwordx4 v[154:157], v[210:211], off offset:-4096
	s_waitcnt vmcnt(15)
	v_mfma_f32_32x32x16_bf16 v[50:65], v[120:123], v[158:161], v[50:65]
	ds_read_b128 v[100:103], v68 offset:7680
	ds_read_b128 v[120:123], v68 offset:6912
	v_mfma_f32_32x32x16_bf16 v[34:49], v[128:131], v[158:161], v[34:49]
	v_mfma_f32_32x32x16_bf16 v[18:33], v[132:135], v[158:161], v[18:33]
	s_waitcnt lgkmcnt(2)
	v_mfma_f32_32x32x16_bf16 v[2:17], v[136:139], v[158:161], v[2:17]
	global_load_dwordx4 v[158:161], v[210:211], off offset:-3072
	s_waitcnt vmcnt(15) lgkmcnt(1)
	v_mfma_f32_32x32x16_bf16 v[50:65], v[100:103], v[162:165], v[50:65]
	ds_read_b128 v[100:103], v68 offset:19968
	ds_read_b128 v[128:131], v68 offset:19200
	s_waitcnt lgkmcnt(1)
	v_mfma_f32_32x32x16_bf16 v[34:49], v[100:103], v[162:165], v[34:49]
	ds_read_b128 v[100:103], v68 offset:32256
	ds_read_b128 v[132:135], v68 offset:31488
	s_waitcnt lgkmcnt(1)
	v_mfma_f32_32x32x16_bf16 v[18:33], v[100:103], v[162:165], v[18:33]
	ds_read_b128 v[100:103], v68 offset:44544
	ds_read_b128 v[136:139], v68 offset:43776
	s_waitcnt lgkmcnt(1)
	v_mfma_f32_32x32x16_bf16 v[2:17], v[100:103], v[162:165], v[2:17]
	global_load_dwordx4 v[162:165], v[210:211], off offset:-2048
	s_waitcnt vmcnt(15)
	v_mfma_f32_32x32x16_bf16 v[50:65], v[120:123], v[166:169], v[50:65]
	ds_read_b128 v[100:103], v68 offset:6144
	ds_read_b128 v[120:123], v68 offset:5376
	v_mfma_f32_32x32x16_bf16 v[34:49], v[128:131], v[166:169], v[34:49]
	v_mfma_f32_32x32x16_bf16 v[18:33], v[132:135], v[166:169], v[18:33]
	s_waitcnt lgkmcnt(2)
	v_mfma_f32_32x32x16_bf16 v[2:17], v[136:139], v[166:169], v[2:17]
	global_load_dwordx4 v[166:169], v[210:211], off offset:-1024
	s_waitcnt vmcnt(15) lgkmcnt(1)
	v_mfma_f32_32x32x16_bf16 v[50:65], v[100:103], v[170:173], v[50:65]
	ds_read_b128 v[100:103], v68 offset:18432
	ds_read_b128 v[124:127], v68 offset:17664
	s_waitcnt lgkmcnt(1)
	v_mfma_f32_32x32x16_bf16 v[34:49], v[100:103], v[170:173], v[34:49]
	ds_read_b128 v[100:103], v68 offset:30720
	ds_read_b128 v[128:131], v68 offset:29952
	s_waitcnt lgkmcnt(1)
	v_mfma_f32_32x32x16_bf16 v[18:33], v[100:103], v[170:173], v[18:33]
	ds_read_b128 v[100:103], v68 offset:43008
	ds_read_b128 v[132:135], v68 offset:42240
	s_waitcnt lgkmcnt(1)
	v_mfma_f32_32x32x16_bf16 v[2:17], v[100:103], v[170:173], v[2:17]
	global_load_dwordx4 v[170:173], v[210:211], off offset:0
	ds_read_b128 v[84:87], v68 offset:4608
	ds_read_b128 v[100:103], v68 offset:3840
	s_waitcnt vmcnt(15)
	v_mfma_f32_32x32x16_bf16 v[50:65], v[120:123], v[174:177], v[50:65]
	v_mfma_f32_32x32x16_bf16 v[34:49], v[124:127], v[174:177], v[34:49]
	v_mfma_f32_32x32x16_bf16 v[18:33], v[128:131], v[174:177], v[18:33]
	s_waitcnt lgkmcnt(2)
	v_mfma_f32_32x32x16_bf16 v[2:17], v[132:135], v[174:177], v[2:17]
	global_load_dwordx4 v[174:177], v[210:211], off offset:1024
	s_waitcnt vmcnt(15) lgkmcnt(1)
; #define GAS __attribute__((address_space(1)))
; #define LAS __attribute__((address_space(3)))
; __device__ __forceinline__ void ph_s5_out(Frame& F) {
;     ...
;         for (int s0 = 0; s0 < 64; s0 += 16) {
;             bf16x8_t bq[16];
; #pragma unroll
;             for (int e = 0; e < 16; ++e) bq[e] = *(const GAS bf16x8_t*)(ub + 512 * (s0 + e));
; #pragma unroll
;             for (int e = 0; e < 16; ++e) { const int sI = s0 + e; const bf16x8_t b = bq[e];
; #pragma unroll
;             for (int i = 0; i < 4; ++i) { const bf16x8_t a = *(const LAS bf16x8_t*)(tl + (16 * i - sI) * 16 * TP_PITCH); acc[i] = __builtin_amdgcn_mfma_f32_32x32x16_bf16(a, b, acc[i], 0, 0, 0); }
;             }
;         }
;         { const bf16* sb = (const bf16*)(ws + WS_SIN) + (size_t)g * 9 * 16 * 512 + ((size_t)nb * 16 * 64 + lane) * 8;
;           const bf16* wc = (const bf16*)(ws + WS_WC) + (size_t)g * 1024 * 256 + (((size_t)wave * 16) * 64 + lane) * 8;
; #pragma unroll 4
;           for (int kk = 0; kk < 16; ++kk) {
;               const bf16x8_t b = *(const GAS bf16x8_t*)(sb + 512 * kk);
; #pragma unroll
;               for (int i = 0; i < 4; ++i) { const bf16x8_t a = *(const GAS bf16x8_t*)(wc + (size_t)(8 * i) * 16 * 512 + 512 * kk); acc[i] = __builtin_amdgcn_mfma_f32_32x32x16_bf16(a, b, acc[i], 0, 0, 0); }
;           } }
	v_mfma_f32_32x32x16_bf16 v[50:65], v[84:87], v[178:181], v[50:65]
	ds_read_b128 v[84:87], v68 offset:16896
	ds_read_b128 v[124:127], v68 offset:16128
	s_waitcnt lgkmcnt(1)
	v_mfma_f32_32x32x16_bf16 v[34:49], v[84:87], v[178:181], v[34:49]
	ds_read_b128 v[84:87], v68 offset:29184
	ds_read_b128 v[128:131], v68 offset:28416
	s_waitcnt lgkmcnt(1)
	v_mfma_f32_32x32x16_bf16 v[18:33], v[84:87], v[178:181], v[18:33]
	ds_read_b128 v[84:87], v68 offset:41472
	ds_read_b128 v[132:135], v68 offset:40704
	s_waitcnt lgkmcnt(1)
	v_mfma_f32_32x32x16_bf16 v[2:17], v[84:87], v[178:181], v[2:17]
	global_load_dwordx4 v[178:181], v[210:211], off offset:2048
	s_waitcnt vmcnt(15)
	v_mfma_f32_32x32x16_bf16 v[50:65], v[100:103], v[182:185], v[50:65]
	v_mfma_f32_32x32x16_bf16 v[34:49], v[124:127], v[182:185], v[34:49]
	v_mfma_f32_32x32x16_bf16 v[18:33], v[128:131], v[182:185], v[18:33]
	s_waitcnt lgkmcnt(0)
	v_mfma_f32_32x32x16_bf16 v[2:17], v[132:135], v[182:185], v[2:17]
	global_load_dwordx4 v[182:185], v[210:211], off offset:3072
	ds_read_b128 v[104:107], v68 offset:3072
	ds_read_b128 v[120:123], v68 offset:2304
	s_waitcnt vmcnt(15) lgkmcnt(1)
	v_mfma_f32_32x32x16_bf16 v[50:65], v[104:107], v[190:193], v[50:65]
	ds_read_b128 v[104:107], v68 offset:15360
	ds_read_b128 v[124:127], v68 offset:14592
	s_waitcnt lgkmcnt(1)
	v_mfma_f32_32x32x16_bf16 v[34:49], v[104:107], v[190:193], v[34:49]
	ds_read_b128 v[104:107], v68 offset:27648
	ds_read_b128 v[128:131], v68 offset:26880
	s_waitcnt lgkmcnt(1)
	v_mfma_f32_32x32x16_bf16 v[18:33], v[104:107], v[190:193], v[18:33]
	ds_read_b128 v[104:107], v68 offset:39936
	ds_read_b128 v[132:135], v68 offset:39168
	s_waitcnt lgkmcnt(1)
	v_mfma_f32_32x32x16_bf16 v[2:17], v[104:107], v[190:193], v[2:17]
	global_load_dwordx4 v[190:193], v[212:213], off offset:-4096
	s_waitcnt vmcnt(15)
	v_mfma_f32_32x32x16_bf16 v[50:65], v[120:123], v[194:197], v[50:65]
	v_mfma_f32_32x32x16_bf16 v[34:49], v[124:127], v[194:197], v[34:49]
	v_mfma_f32_32x32x16_bf16 v[18:33], v[128:131], v[194:197], v[18:33]
	s_waitcnt lgkmcnt(0)
	v_mfma_f32_32x32x16_bf16 v[2:17], v[132:135], v[194:197], v[2:17]
	global_load_dwordx4 v[194:197], v[212:213], off offset:-3072
	ds_read_b128 v[100:103], v68 offset:1536
	ds_read_b128 v[120:123], v68 offset:768
	s_waitcnt vmcnt(15) lgkmcnt(1)
	v_mfma_f32_32x32x16_bf16 v[50:65], v[100:103], v[198:201], v[50:65]
	ds_read_b128 v[100:103], v68 offset:13824
	ds_read_b128 v[124:127], v68 offset:13056
	s_waitcnt lgkmcnt(1)
	v_mfma_f32_32x32x16_bf16 v[34:49], v[100:103], v[198:201], v[34:49]
	ds_read_b128 v[100:103], v68 offset:26112
	ds_read_b128 v[128:131], v68 offset:25344
	s_waitcnt lgkmcnt(1)
	v_mfma_f32_32x32x16_bf16 v[18:33], v[100:103], v[198:201], v[18:33]
	ds_read_b128 v[100:103], v68 offset:38400
	ds_read_b128 v[132:135], v68 offset:37632
	v_add_u32_e32 v68, 0xffffd000, v68
	s_waitcnt lgkmcnt(1)
	v_mfma_f32_32x32x16_bf16 v[2:17], v[100:103], v[198:201], v[2:17]
	global_load_dwordx4 v[198:201], v[212:213], off offset:-2048
	s_waitcnt vmcnt(15)
	v_mfma_f32_32x32x16_bf16 v[50:65], v[120:123], v[202:205], v[50:65]
	v_mfma_f32_32x32x16_bf16 v[34:49], v[124:127], v[202:205], v[34:49]
	v_mfma_f32_32x32x16_bf16 v[18:33], v[128:131], v[202:205], v[18:33]
	s_waitcnt lgkmcnt(0)
	v_mfma_f32_32x32x16_bf16 v[2:17], v[132:135], v[202:205], v[2:17]
	global_load_dwordx4 v[202:205], v[212:213], off offset:-1024
	s_waitcnt vmcnt(15)
	v_mfma_f32_32x32x16_bf16 v[50:65], v[116:119], v[206:209], v[50:65]
	v_mfma_f32_32x32x16_bf16 v[34:49], v[96:99], v[206:209], v[34:49]
	v_mfma_f32_32x32x16_bf16 v[18:33], v[108:111], v[206:209], v[18:33]
	v_mfma_f32_32x32x16_bf16 v[2:17], v[112:115], v[206:209], v[2:17]
	global_load_dwordx4 v[206:209], v[212:213], off offset:0
	v_lshl_add_u64 v[82:83], v[82:83], 0, s[22:23]
	s_add_i32 s25, s25, 16
	s_cmp_gt_u32 s25, 31
	s_cbranch_scc0 .LBB0_972
	s_ashr_i32 s25, s24, 31
	s_mul_i32 s49, s26, 0x24000
	s_lshl_b64 s[28:29], s[24:25], 14
	s_lshl_b64 s[34:35], s[26:27], 19
	s_mul_hi_i32 s31, s26, 0x24000
	s_add_u32 s28, s49, s28
	s_addc_u32 s29, s31, s29
	s_add_u32 s28, s28, 0x800
	s_addc_u32 s29, s29, 0
	s_add_u32 s34, s34, 0x9901000
	s_addc_u32 s35, s35, 0
	v_lshl_add_u64 v[88:89], v[80:81], 0, s[28:29]
	v_lshl_add_u64 v[214:215], v[78:79], 0, s[34:35]
	s_mov_b64 s[28:29], 0x20000
	v_lshl_add_u64 v[216:217], v[214:215], 0, s[28:29]
	v_lshl_add_u64 v[140:141], v[216:217], 0, s[28:29]
	v_lshl_add_u64 v[186:187], v[140:141], 0, s[28:29]
	ds_read_b128 v[84:87], v68 offset:11520
	ds_read_b128 v[96:99], v68 offset:12288
	s_waitcnt vmcnt(15) lgkmcnt(1)
	v_mfma_f32_32x32x16_bf16 v[50:65], v[84:87], v[142:145], v[50:65]
	ds_read_b128 v[84:87], v68 offset:23808
	ds_read_b128 v[108:111], v68 offset:24576
	s_waitcnt lgkmcnt(1)
	v_mfma_f32_32x32x16_bf16 v[34:49], v[84:87], v[142:145], v[34:49]
	ds_read_b128 v[84:87], v68 offset:36096
	ds_read_b128 v[112:115], v68 offset:36864
	s_waitcnt lgkmcnt(1)
	v_mfma_f32_32x32x16_bf16 v[18:33], v[84:87], v[142:145], v[18:33]
	ds_read_b128 v[84:87], v68 offset:48384
	ds_read_b128 v[116:119], v68
	s_waitcnt lgkmcnt(1)
	v_mfma_f32_32x32x16_bf16 v[2:17], v[84:87], v[142:145], v[2:17]
	global_load_dwordx4 v[142:145], v[88:89], off offset:-4096
	ds_read_b128 v[84:87], v68 offset:10752
	ds_read_b128 v[100:103], v68 offset:9984
	s_waitcnt vmcnt(15) lgkmcnt(1)
	v_mfma_f32_32x32x16_bf16 v[50:65], v[84:87], v[146:149], v[50:65]
	ds_read_b128 v[84:87], v68 offset:23040
	ds_read_b128 v[120:123], v68 offset:22272
	s_waitcnt lgkmcnt(1)
	v_mfma_f32_32x32x16_bf16 v[34:49], v[84:87], v[146:149], v[34:49]
	ds_read_b128 v[84:87], v68 offset:35328
	ds_read_b128 v[124:127], v68 offset:34560
	ds_read_b128 v[128:131], v68 offset:46848
	s_waitcnt lgkmcnt(2)
; #define GAS __attribute__((address_space(1)))
; #define LAS __attribute__((address_space(3)))
; __device__ __forceinline__ void ph_s5_out(Frame& F) {
;     ...
;         for (int s0 = 0; s0 < 64; s0 += 16) {
;             bf16x8_t bq[16];
; #pragma unroll
;             for (int e = 0; e < 16; ++e) bq[e] = *(const GAS bf16x8_t*)(ub + 512 * (s0 + e));
; #pragma unroll
;             for (int e = 0; e < 16; ++e) { const int sI = s0 + e; const bf16x8_t b = bq[e];
; #pragma unroll
;             for (int i = 0; i < 4; ++i) { const bf16x8_t a = *(const LAS bf16x8_t*)(tl + (16 * i - sI) * 16 * TP_PITCH); acc[i] = __builtin_amdgcn_mfma_f32_32x32x16_bf16(a, b, acc[i], 0, 0, 0); }
;             }
;         }
;         { const bf16* sb = (const bf16*)(ws + WS_SIN) + (size_t)g * 9 * 16 * 512 + ((size_t)nb * 16 * 64 + lane) * 8;
;           const bf16* wc = (const bf16*)(ws + WS_WC) + (size_t)g * 1024 * 256 + (((size_t)wave * 16) * 64 + lane) * 8;
; #pragma unroll 4
;           for (int kk = 0; kk < 16; ++kk) {
;               const bf16x8_t b = *(const GAS bf16x8_t*)(sb + 512 * kk);
; #pragma unroll
;               for (int i = 0; i < 4; ++i) { const bf16x8_t a = *(const GAS bf16x8_t*)(wc + (size_t)(8 * i) * 16 * 512 + 512 * kk); acc[i] = __builtin_amdgcn_mfma_f32_32x32x16_bf16(a, b, acc[i], 0, 0, 0); }
;           } }
	v_mfma_f32_32x32x16_bf16 v[18:33], v[84:87], v[146:149], v[18:33]
	ds_read_b128 v[84:87], v68 offset:47616
	s_waitcnt lgkmcnt(0)
	v_mfma_f32_32x32x16_bf16 v[2:17], v[84:87], v[146:149], v[2:17]
	global_load_dwordx4 v[146:149], v[214:215], off offset:-4096
	s_waitcnt vmcnt(15)
	v_mfma_f32_32x32x16_bf16 v[50:65], v[100:103], v[150:153], v[50:65]
	v_mfma_f32_32x32x16_bf16 v[34:49], v[120:123], v[150:153], v[34:49]
	ds_read_b128 v[100:103], v68 offset:9216
	ds_read_b128 v[120:123], v68 offset:8448
	v_mfma_f32_32x32x16_bf16 v[18:33], v[124:127], v[150:153], v[18:33]
	v_mfma_f32_32x32x16_bf16 v[2:17], v[128:131], v[150:153], v[2:17]
	global_load_dwordx4 v[150:153], v[216:217], off offset:-4096
	s_waitcnt vmcnt(15) lgkmcnt(1)
	v_mfma_f32_32x32x16_bf16 v[50:65], v[100:103], v[154:157], v[50:65]
	ds_read_b128 v[100:103], v68 offset:21504
	ds_read_b128 v[128:131], v68 offset:20736
	s_waitcnt lgkmcnt(1)
	v_mfma_f32_32x32x16_bf16 v[34:49], v[100:103], v[154:157], v[34:49]
	ds_read_b128 v[100:103], v68 offset:33792
	ds_read_b128 v[132:135], v68 offset:33024
	s_waitcnt lgkmcnt(1)
	v_mfma_f32_32x32x16_bf16 v[18:33], v[100:103], v[154:157], v[18:33]
	ds_read_b128 v[100:103], v68 offset:46080
	ds_read_b128 v[136:139], v68 offset:45312
	s_waitcnt lgkmcnt(1)
	v_mfma_f32_32x32x16_bf16 v[2:17], v[100:103], v[154:157], v[2:17]
	global_load_dwordx4 v[154:157], v[140:141], off offset:-4096
	s_waitcnt vmcnt(15)
	v_mfma_f32_32x32x16_bf16 v[50:65], v[120:123], v[158:161], v[50:65]
	ds_read_b128 v[100:103], v68 offset:7680
	ds_read_b128 v[120:123], v68 offset:6912
	v_mfma_f32_32x32x16_bf16 v[34:49], v[128:131], v[158:161], v[34:49]
	v_mfma_f32_32x32x16_bf16 v[18:33], v[132:135], v[158:161], v[18:33]
	s_waitcnt lgkmcnt(2)
	v_mfma_f32_32x32x16_bf16 v[2:17], v[136:139], v[158:161], v[2:17]
	global_load_dwordx4 v[158:161], v[186:187], off offset:-4096
	s_waitcnt vmcnt(15) lgkmcnt(1)
	v_mfma_f32_32x32x16_bf16 v[50:65], v[100:103], v[162:165], v[50:65]
	ds_read_b128 v[100:103], v68 offset:19968
	ds_read_b128 v[128:131], v68 offset:19200
	s_waitcnt lgkmcnt(1)
	v_mfma_f32_32x32x16_bf16 v[34:49], v[100:103], v[162:165], v[34:49]
	ds_read_b128 v[100:103], v68 offset:32256
	ds_read_b128 v[132:135], v68 offset:31488
	s_waitcnt lgkmcnt(1)
	v_mfma_f32_32x32x16_bf16 v[18:33], v[100:103], v[162:165], v[18:33]
	ds_read_b128 v[100:103], v68 offset:44544
	ds_read_b128 v[136:139], v68 offset:43776
	s_waitcnt lgkmcnt(1)
	v_mfma_f32_32x32x16_bf16 v[2:17], v[100:103], v[162:165], v[2:17]
	global_load_dwordx4 v[162:165], v[88:89], off offset:-3072
	s_waitcnt vmcnt(15)
	v_mfma_f32_32x32x16_bf16 v[50:65], v[120:123], v[166:169], v[50:65]
	ds_read_b128 v[100:103], v68 offset:6144
	ds_read_b128 v[120:123], v68 offset:5376
	v_mfma_f32_32x32x16_bf16 v[34:49], v[128:131], v[166:169], v[34:49]
	v_mfma_f32_32x32x16_bf16 v[18:33], v[132:135], v[166:169], v[18:33]
	s_waitcnt lgkmcnt(2)
	v_mfma_f32_32x32x16_bf16 v[2:17], v[136:139], v[166:169], v[2:17]
	global_load_dwordx4 v[166:169], v[214:215], off offset:-3072
	s_waitcnt vmcnt(15) lgkmcnt(1)
	v_mfma_f32_32x32x16_bf16 v[50:65], v[100:103], v[170:173], v[50:65]
	ds_read_b128 v[100:103], v68 offset:18432
	ds_read_b128 v[124:127], v68 offset:17664
	s_waitcnt lgkmcnt(1)
	v_mfma_f32_32x32x16_bf16 v[34:49], v[100:103], v[170:173], v[34:49]
	ds_read_b128 v[100:103], v68 offset:30720
	ds_read_b128 v[128:131], v68 offset:29952
	s_waitcnt lgkmcnt(1)
	v_mfma_f32_32x32x16_bf16 v[18:33], v[100:103], v[170:173], v[18:33]
	ds_read_b128 v[100:103], v68 offset:43008
	ds_read_b128 v[132:135], v68 offset:42240
	s_waitcnt lgkmcnt(1)
	v_mfma_f32_32x32x16_bf16 v[2:17], v[100:103], v[170:173], v[2:17]
	global_load_dwordx4 v[170:173], v[216:217], off offset:-3072
	ds_read_b128 v[84:87], v68 offset:4608
	ds_read_b128 v[100:103], v68 offset:3840
	s_waitcnt vmcnt(15)
	v_mfma_f32_32x32x16_bf16 v[50:65], v[120:123], v[174:177], v[50:65]
	v_mfma_f32_32x32x16_bf16 v[34:49], v[124:127], v[174:177], v[34:49]
	v_mfma_f32_32x32x16_bf16 v[18:33], v[128:131], v[174:177], v[18:33]
	s_waitcnt lgkmcnt(2)
	v_mfma_f32_32x32x16_bf16 v[2:17], v[132:135], v[174:177], v[2:17]
	global_load_dwordx4 v[174:177], v[140:141], off offset:-3072
	s_waitcnt vmcnt(15) lgkmcnt(1)
	v_mfma_f32_32x32x16_bf16 v[50:65], v[84:87], v[178:181], v[50:65]
	ds_read_b128 v[84:87], v68 offset:16896
	ds_read_b128 v[124:127], v68 offset:16128
	s_waitcnt lgkmcnt(1)
	v_mfma_f32_32x32x16_bf16 v[34:49], v[84:87], v[178:181], v[34:49]
	ds_read_b128 v[84:87], v68 offset:29184
	ds_read_b128 v[128:131], v68 offset:28416
	s_waitcnt lgkmcnt(1)
	v_mfma_f32_32x32x16_bf16 v[18:33], v[84:87], v[178:181], v[18:33]
	ds_read_b128 v[84:87], v68 offset:41472
	ds_read_b128 v[132:135], v68 offset:40704
	s_waitcnt lgkmcnt(1)
	v_mfma_f32_32x32x16_bf16 v[2:17], v[84:87], v[178:181], v[2:17]
	global_load_dwordx4 v[178:181], v[186:187], off offset:-3072
	s_waitcnt vmcnt(15)
	v_mfma_f32_32x32x16_bf16 v[50:65], v[100:103], v[182:185], v[50:65]
	v_mfma_f32_32x32x16_bf16 v[34:49], v[124:127], v[182:185], v[34:49]
	v_mfma_f32_32x32x16_bf16 v[18:33], v[128:131], v[182:185], v[18:33]
	s_waitcnt lgkmcnt(0)
	v_mfma_f32_32x32x16_bf16 v[2:17], v[132:135], v[182:185], v[2:17]
	global_load_dwordx4 v[182:185], v[88:89], off offset:-2048
	ds_read_b128 v[104:107], v68 offset:3072
	ds_read_b128 v[120:123], v68 offset:2304
	s_waitcnt vmcnt(15) lgkmcnt(1)
	v_mfma_f32_32x32x16_bf16 v[50:65], v[104:107], v[190:193], v[50:65]
	ds_read_b128 v[104:107], v68 offset:15360
	ds_read_b128 v[124:127], v68 offset:14592
	s_waitcnt lgkmcnt(1)
	v_mfma_f32_32x32x16_bf16 v[34:49], v[104:107], v[190:193], v[34:49]
	ds_read_b128 v[104:107], v68 offset:27648
	ds_read_b128 v[128:131], v68 offset:26880
	s_waitcnt lgkmcnt(1)
; #define GAS __attribute__((address_space(1)))
; __device__ __forceinline__ void ph_s5_out(Frame& F) {
;     ...
;         { const bf16* sb = (const bf16*)(ws + WS_SIN) + (size_t)g * 9 * 16 * 512 + ((size_t)nb * 16 * 64 + lane) * 8;
;           const bf16* wc = (const bf16*)(ws + WS_WC) + (size_t)g * 1024 * 256 + (((size_t)wave * 16) * 64 + lane) * 8;
; #pragma unroll 4
;           for (int kk = 0; kk < 16; ++kk) {
;               const bf16x8_t b = *(const GAS bf16x8_t*)(sb + 512 * kk);
; #pragma unroll
;               for (int i = 0; i < 4; ++i) { const bf16x8_t a = *(const GAS bf16x8_t*)(wc + (size_t)(8 * i) * 16 * 512 + 512 * kk); acc[i] = __builtin_amdgcn_mfma_f32_32x32x16_bf16(a, b, acc[i], 0, 0, 0); }
;           } }
	v_mfma_f32_32x32x16_bf16 v[18:33], v[104:107], v[190:193], v[18:33]
	ds_read_b128 v[104:107], v68 offset:39936
	ds_read_b128 v[132:135], v68 offset:39168
	s_waitcnt lgkmcnt(1)
	v_mfma_f32_32x32x16_bf16 v[2:17], v[104:107], v[190:193], v[2:17]
	global_load_dwordx4 v[190:193], v[214:215], off offset:-2048
	s_waitcnt vmcnt(15)
	v_mfma_f32_32x32x16_bf16 v[50:65], v[120:123], v[194:197], v[50:65]
	v_mfma_f32_32x32x16_bf16 v[34:49], v[124:127], v[194:197], v[34:49]
	v_mfma_f32_32x32x16_bf16 v[18:33], v[128:131], v[194:197], v[18:33]
	s_waitcnt lgkmcnt(0)
	v_mfma_f32_32x32x16_bf16 v[2:17], v[132:135], v[194:197], v[2:17]
	global_load_dwordx4 v[194:197], v[216:217], off offset:-2048
	ds_read_b128 v[100:103], v68 offset:1536
	ds_read_b128 v[120:123], v68 offset:768
	s_waitcnt vmcnt(15) lgkmcnt(1)
	v_mfma_f32_32x32x16_bf16 v[50:65], v[100:103], v[198:201], v[50:65]
	ds_read_b128 v[100:103], v68 offset:13824
	ds_read_b128 v[124:127], v68 offset:13056
	s_waitcnt lgkmcnt(1)
	v_mfma_f32_32x32x16_bf16 v[34:49], v[100:103], v[198:201], v[34:49]
	ds_read_b128 v[100:103], v68 offset:26112
	ds_read_b128 v[128:131], v68 offset:25344
	s_waitcnt lgkmcnt(1)
	v_mfma_f32_32x32x16_bf16 v[18:33], v[100:103], v[198:201], v[18:33]
	ds_read_b128 v[100:103], v68 offset:38400
	ds_read_b128 v[132:135], v68 offset:37632
	v_add_u32_e32 v68, 0xffffd000, v68
	s_waitcnt lgkmcnt(1)
	v_mfma_f32_32x32x16_bf16 v[2:17], v[100:103], v[198:201], v[2:17]
	global_load_dwordx4 v[198:201], v[140:141], off offset:-2048
	s_waitcnt vmcnt(15)
	v_mfma_f32_32x32x16_bf16 v[50:65], v[120:123], v[202:205], v[50:65]
	v_mfma_f32_32x32x16_bf16 v[34:49], v[124:127], v[202:205], v[34:49]
	v_mfma_f32_32x32x16_bf16 v[18:33], v[128:131], v[202:205], v[18:33]
	s_waitcnt lgkmcnt(0)
	v_mfma_f32_32x32x16_bf16 v[2:17], v[132:135], v[202:205], v[2:17]
	global_load_dwordx4 v[202:205], v[186:187], off offset:-2048
	s_waitcnt vmcnt(15)
	v_mfma_f32_32x32x16_bf16 v[50:65], v[116:119], v[206:209], v[50:65]
	v_mfma_f32_32x32x16_bf16 v[34:49], v[96:99], v[206:209], v[34:49]
	v_mfma_f32_32x32x16_bf16 v[18:33], v[108:111], v[206:209], v[18:33]
	v_mfma_f32_32x32x16_bf16 v[2:17], v[112:115], v[206:209], v[2:17]
	global_load_dwordx4 v[206:209], v[88:89], off offset:-1024
	global_load_dwordx4 v[96:99], v[214:215], off offset:-1024
	global_load_dwordx4 v[100:103], v[216:217], off offset:-1024
	global_load_dwordx4 v[104:107], v[140:141], off offset:-1024
	global_load_dwordx4 v[108:111], v[186:187], off offset:-1024
	global_load_dwordx4 v[112:115], v[88:89], off
	global_load_dwordx4 v[116:119], v[214:215], off
	global_load_dwordx4 v[120:123], v[216:217], off
	global_load_dwordx4 v[124:127], v[140:141], off
	global_load_dwordx4 v[128:131], v[186:187], off
	global_load_dwordx4 v[132:135], v[88:89], off offset:1024
	global_load_dwordx4 v[136:139], v[214:215], off offset:1024
	s_waitcnt vmcnt(25)
	v_mfma_f32_32x32x16_bf16 v[50:65], v[146:149], v[142:145], v[50:65]
	global_load_dwordx4 v[146:149], v[216:217], off offset:1024
	s_waitcnt vmcnt(25)
	v_mfma_f32_32x32x16_bf16 v[34:49], v[150:153], v[142:145], v[34:49]
	global_load_dwordx4 v[150:153], v[140:141], off offset:1024
	s_waitcnt vmcnt(25)
	v_mfma_f32_32x32x16_bf16 v[18:33], v[154:157], v[142:145], v[18:33]
	global_load_dwordx4 v[154:157], v[186:187], off offset:1024
	s_waitcnt vmcnt(25)
	v_mfma_f32_32x32x16_bf16 v[2:17], v[158:161], v[142:145], v[2:17]
	global_load_dwordx4 v[158:161], v[88:89], off offset:2048
	global_load_dwordx4 v[142:145], v[214:215], off offset:2048
	s_waitcnt vmcnt(25)
	v_mfma_f32_32x32x16_bf16 v[50:65], v[166:169], v[162:165], v[50:65]
	global_load_dwordx4 v[166:169], v[216:217], off offset:2048
	s_waitcnt vmcnt(25)
	v_mfma_f32_32x32x16_bf16 v[34:49], v[170:173], v[162:165], v[34:49]
	global_load_dwordx4 v[170:173], v[140:141], off offset:2048
	s_waitcnt vmcnt(25)
	v_mfma_f32_32x32x16_bf16 v[18:33], v[174:177], v[162:165], v[18:33]
	global_load_dwordx4 v[174:177], v[186:187], off offset:2048
	s_waitcnt vmcnt(25)
	v_mfma_f32_32x32x16_bf16 v[2:17], v[178:181], v[162:165], v[2:17]
	global_load_dwordx4 v[178:181], v[88:89], off offset:3072
	global_load_dwordx4 v[162:165], v[214:215], off offset:3072
	s_waitcnt vmcnt(25)
	v_mfma_f32_32x32x16_bf16 v[50:65], v[190:193], v[182:185], v[50:65]
	global_load_dwordx4 v[190:193], v[216:217], off offset:3072
	s_waitcnt vmcnt(25)
	v_mfma_f32_32x32x16_bf16 v[34:49], v[194:197], v[182:185], v[34:49]
	global_load_dwordx4 v[194:197], v[140:141], off offset:3072
	s_waitcnt vmcnt(25)
	v_mfma_f32_32x32x16_bf16 v[18:33], v[198:201], v[182:185], v[18:33]
	global_load_dwordx4 v[198:201], v[186:187], off offset:3072
	s_waitcnt vmcnt(25)
	v_mfma_f32_32x32x16_bf16 v[2:17], v[202:205], v[182:185], v[2:17]
	v_lshl_add_u64 v[88:89], v[88:89], 0, s[20:21]
	v_lshl_add_u64 v[214:215], v[214:215], 0, s[20:21]
	v_lshl_add_u64 v[216:217], v[216:217], 0, s[20:21]
	v_lshl_add_u64 v[140:141], v[140:141], 0, s[20:21]
	v_lshl_add_u64 v[186:187], v[186:187], 0, s[20:21]
	global_load_dwordx4 v[202:205], v[88:89], off offset:-4096
	global_load_dwordx4 v[182:185], v[214:215], off offset:-4096
	s_waitcnt vmcnt(25)
	v_mfma_f32_32x32x16_bf16 v[50:65], v[96:99], v[206:209], v[50:65]
	global_load_dwordx4 v[96:99], v[216:217], off offset:-4096
	s_waitcnt vmcnt(25)
	v_mfma_f32_32x32x16_bf16 v[34:49], v[100:103], v[206:209], v[34:49]
	global_load_dwordx4 v[100:103], v[140:141], off offset:-4096
	s_waitcnt vmcnt(25)
	v_mfma_f32_32x32x16_bf16 v[18:33], v[104:107], v[206:209], v[18:33]
	global_load_dwordx4 v[104:107], v[186:187], off offset:-4096
	s_waitcnt vmcnt(25)
; #define GAS __attribute__((address_space(1)))
; __device__ __forceinline__ void ph_s5_out(Frame& F) {
;     ...
;         { const bf16* sb = (const bf16*)(ws + WS_SIN) + (size_t)g * 9 * 16 * 512 + ((size_t)nb * 16 * 64 + lane) * 8;
;           const bf16* wc = (const bf16*)(ws + WS_WC) + (size_t)g * 1024 * 256 + (((size_t)wave * 16) * 64 + lane) * 8;
; #pragma unroll 4
;           for (int kk = 0; kk < 16; ++kk) {
;               const bf16x8_t b = *(const GAS bf16x8_t*)(sb + 512 * kk);
; #pragma unroll
;               for (int i = 0; i < 4; ++i) { const bf16x8_t a = *(const GAS bf16x8_t*)(wc + (size_t)(8 * i) * 16 * 512 + 512 * kk); acc[i] = __builtin_amdgcn_mfma_f32_32x32x16_bf16(a, b, acc[i], 0, 0, 0); }
;           } }
;         if (valid) {
	v_mfma_f32_32x32x16_bf16 v[2:17], v[108:111], v[206:209], v[2:17]
	global_load_dwordx4 v[108:111], v[88:89], off offset:-3072
	global_load_dwordx4 v[206:209], v[214:215], off offset:-3072
	s_waitcnt vmcnt(25)
	v_mfma_f32_32x32x16_bf16 v[50:65], v[116:119], v[112:115], v[50:65]
	global_load_dwordx4 v[116:119], v[216:217], off offset:-3072
	s_waitcnt vmcnt(25)
	v_mfma_f32_32x32x16_bf16 v[34:49], v[120:123], v[112:115], v[34:49]
	global_load_dwordx4 v[120:123], v[140:141], off offset:-3072
	s_waitcnt vmcnt(25)
	v_mfma_f32_32x32x16_bf16 v[18:33], v[124:127], v[112:115], v[18:33]
	global_load_dwordx4 v[124:127], v[186:187], off offset:-3072
	s_waitcnt vmcnt(25)
	v_mfma_f32_32x32x16_bf16 v[2:17], v[128:131], v[112:115], v[2:17]
	global_load_dwordx4 v[128:131], v[88:89], off offset:-2048
	global_load_dwordx4 v[112:115], v[214:215], off offset:-2048
	s_waitcnt vmcnt(25)
	v_mfma_f32_32x32x16_bf16 v[50:65], v[136:139], v[132:135], v[50:65]
	global_load_dwordx4 v[136:139], v[216:217], off offset:-2048
	s_waitcnt vmcnt(25)
	v_mfma_f32_32x32x16_bf16 v[34:49], v[146:149], v[132:135], v[34:49]
	global_load_dwordx4 v[146:149], v[140:141], off offset:-2048
	s_waitcnt vmcnt(25)
	v_mfma_f32_32x32x16_bf16 v[18:33], v[150:153], v[132:135], v[18:33]
	global_load_dwordx4 v[150:153], v[186:187], off offset:-2048
	s_waitcnt vmcnt(25)
	v_mfma_f32_32x32x16_bf16 v[2:17], v[154:157], v[132:135], v[2:17]
	global_load_dwordx4 v[154:157], v[88:89], off offset:-1024
	global_load_dwordx4 v[132:135], v[214:215], off offset:-1024
	s_waitcnt vmcnt(25)
	v_mfma_f32_32x32x16_bf16 v[50:65], v[142:145], v[158:161], v[50:65]
	global_load_dwordx4 v[142:145], v[216:217], off offset:-1024
	s_waitcnt vmcnt(25)
	v_mfma_f32_32x32x16_bf16 v[34:49], v[166:169], v[158:161], v[34:49]
	global_load_dwordx4 v[166:169], v[140:141], off offset:-1024
	s_waitcnt vmcnt(25)
	v_mfma_f32_32x32x16_bf16 v[18:33], v[170:173], v[158:161], v[18:33]
	global_load_dwordx4 v[170:173], v[186:187], off offset:-1024
	s_waitcnt vmcnt(25)
	v_mfma_f32_32x32x16_bf16 v[2:17], v[174:177], v[158:161], v[2:17]
	global_load_dwordx4 v[174:177], v[88:89], off
	global_load_dwordx4 v[158:161], v[214:215], off
	s_waitcnt vmcnt(25)
	v_mfma_f32_32x32x16_bf16 v[50:65], v[162:165], v[178:181], v[50:65]
	global_load_dwordx4 v[162:165], v[216:217], off
	s_waitcnt vmcnt(25)
	v_mfma_f32_32x32x16_bf16 v[34:49], v[190:193], v[178:181], v[34:49]
	global_load_dwordx4 v[190:193], v[140:141], off
	s_waitcnt vmcnt(25)
	v_mfma_f32_32x32x16_bf16 v[18:33], v[194:197], v[178:181], v[18:33]
	global_load_dwordx4 v[194:197], v[186:187], off
	s_waitcnt vmcnt(25)
	v_mfma_f32_32x32x16_bf16 v[2:17], v[198:201], v[178:181], v[2:17]
	global_load_dwordx4 v[198:201], v[88:89], off offset:1024
	global_load_dwordx4 v[178:181], v[214:215], off offset:1024
	s_waitcnt vmcnt(25)
	v_mfma_f32_32x32x16_bf16 v[50:65], v[182:185], v[202:205], v[50:65]
	global_load_dwordx4 v[182:185], v[216:217], off offset:1024
	s_waitcnt vmcnt(25)
	v_mfma_f32_32x32x16_bf16 v[34:49], v[96:99], v[202:205], v[34:49]
	global_load_dwordx4 v[96:99], v[140:141], off offset:1024
	s_waitcnt vmcnt(25)
	v_mfma_f32_32x32x16_bf16 v[18:33], v[100:103], v[202:205], v[18:33]
	global_load_dwordx4 v[100:103], v[186:187], off offset:1024
	s_waitcnt vmcnt(25)
	v_mfma_f32_32x32x16_bf16 v[2:17], v[104:107], v[202:205], v[2:17]
	global_load_dwordx4 v[104:107], v[88:89], off offset:2048
	global_load_dwordx4 v[202:205], v[214:215], off offset:2048
	s_waitcnt vmcnt(25)
	v_mfma_f32_32x32x16_bf16 v[50:65], v[206:209], v[108:111], v[50:65]
	global_load_dwordx4 v[206:209], v[216:217], off offset:2048
	s_waitcnt vmcnt(25)
	v_mfma_f32_32x32x16_bf16 v[34:49], v[116:119], v[108:111], v[34:49]
	global_load_dwordx4 v[116:119], v[140:141], off offset:2048
	s_waitcnt vmcnt(25)
	v_mfma_f32_32x32x16_bf16 v[18:33], v[120:123], v[108:111], v[18:33]
	global_load_dwordx4 v[120:123], v[186:187], off offset:2048
	s_waitcnt vmcnt(25)
	v_mfma_f32_32x32x16_bf16 v[2:17], v[124:127], v[108:111], v[2:17]
	global_load_dwordx4 v[124:127], v[88:89], off offset:3072
	global_load_dwordx4 v[108:111], v[214:215], off offset:3072
	s_waitcnt vmcnt(25)
	v_mfma_f32_32x32x16_bf16 v[50:65], v[112:115], v[128:131], v[50:65]
	global_load_dwordx4 v[112:115], v[216:217], off offset:3072
	s_waitcnt vmcnt(25)
	v_mfma_f32_32x32x16_bf16 v[34:49], v[136:139], v[128:131], v[34:49]
	global_load_dwordx4 v[136:139], v[140:141], off offset:3072
	s_waitcnt vmcnt(25)
	v_mfma_f32_32x32x16_bf16 v[18:33], v[146:149], v[128:131], v[18:33]
	global_load_dwordx4 v[146:149], v[186:187], off offset:3072
	s_waitcnt vmcnt(25)
	v_mfma_f32_32x32x16_bf16 v[2:17], v[150:153], v[128:131], v[2:17]
	s_waitcnt vmcnt(23)
	v_mfma_f32_32x32x16_bf16 v[50:65], v[132:135], v[154:157], v[50:65]
	s_waitcnt vmcnt(22)
	v_mfma_f32_32x32x16_bf16 v[34:49], v[142:145], v[154:157], v[34:49]
	s_waitcnt vmcnt(21)
	v_mfma_f32_32x32x16_bf16 v[18:33], v[166:169], v[154:157], v[18:33]
	s_waitcnt vmcnt(20)
	v_mfma_f32_32x32x16_bf16 v[2:17], v[170:173], v[154:157], v[2:17]
	s_waitcnt vmcnt(18)
	v_mfma_f32_32x32x16_bf16 v[50:65], v[158:161], v[174:177], v[50:65]
	s_waitcnt vmcnt(17)
	v_mfma_f32_32x32x16_bf16 v[34:49], v[162:165], v[174:177], v[34:49]
	s_waitcnt vmcnt(16)
	v_mfma_f32_32x32x16_bf16 v[18:33], v[190:193], v[174:177], v[18:33]
	s_waitcnt vmcnt(15)
	v_mfma_f32_32x32x16_bf16 v[2:17], v[194:197], v[174:177], v[2:17]
	s_waitcnt vmcnt(13)
	v_mfma_f32_32x32x16_bf16 v[50:65], v[178:181], v[198:201], v[50:65]
	s_waitcnt vmcnt(12)
	v_mfma_f32_32x32x16_bf16 v[34:49], v[182:185], v[198:201], v[34:49]
	s_waitcnt vmcnt(11)
	v_mfma_f32_32x32x16_bf16 v[18:33], v[96:99], v[198:201], v[18:33]
	s_waitcnt vmcnt(10)
	v_mfma_f32_32x32x16_bf16 v[2:17], v[100:103], v[198:201], v[2:17]
	s_waitcnt vmcnt(8)
	v_mfma_f32_32x32x16_bf16 v[50:65], v[202:205], v[104:107], v[50:65]
	s_waitcnt vmcnt(7)
	v_mfma_f32_32x32x16_bf16 v[34:49], v[206:209], v[104:107], v[34:49]
	s_waitcnt vmcnt(6)
	v_mfma_f32_32x32x16_bf16 v[18:33], v[116:119], v[104:107], v[18:33]
	s_waitcnt vmcnt(5)
	v_mfma_f32_32x32x16_bf16 v[2:17], v[120:123], v[104:107], v[2:17]
	s_waitcnt vmcnt(3)
	v_mfma_f32_32x32x16_bf16 v[50:65], v[108:111], v[124:127], v[50:65]
	s_waitcnt vmcnt(2)
	v_mfma_f32_32x32x16_bf16 v[34:49], v[112:115], v[124:127], v[34:49]
	s_waitcnt vmcnt(1)
	v_mfma_f32_32x32x16_bf16 v[18:33], v[136:139], v[124:127], v[18:33]
	s_waitcnt vmcnt(0)
	v_mfma_f32_32x32x16_bf16 v[2:17], v[146:149], v[124:127], v[2:17]
	v_lshl_or_b32 v82, s24, 5, v1
	v_cmp_gt_i32_e32 vcc, s45, v82
	s_and_saveexec_b64 s[24:25], vcc
	s_cbranch_execz .LBB0_963
; #define GAS __attribute__((address_space(1)))
; __device__ __forceinline__ unsigned pk2(float lo, float hi) { const f32x2cv v = {lo, hi}; return __builtin_bit_cast(unsigned, __builtin_convertvector(v, bf16x2cv)); }
; __device__ __forceinline__ float gelu_tanh(float x) { const float u = 0.7978845608028654f * (x + 0.044715f * x * x * x); return x * __builtin_amdgcn_rcpf(1.0f + __builtin_amdgcn_exp2f(-2.8853900817779268f * u)); }
; __device__ __forceinline__ void ph_s5_out(Frame& F) {
;     ...
;         if (valid) {
;             const float* dsk = inp(F, 24) + 16 * g;
; #pragma unroll
;             for (int i = 0; i < 4; ++i)
; #pragma unroll
;                 for (int k = 0; k < 4; ++k) { const int tloc = 2 * (wave + 8 * i) + (k >> 1), p0 = 8 * (k & 1) + 4 * hh; const size_t m = (size_t)chunk * 64 + tloc;
;                     const v2u uw = *(const GAS v2u*)((chunk < 256 ? (const bf16*)(ws + WS_UG) : (const bf16*)(ws + WS_UGC)) + ug_index(g, (int)m, p0));
;                     const float y0 = gelu_tanh(acc[i][4 * k] + dsk[p0] * bflo(uw.x)), y1 = gelu_tanh(acc[i][4 * k + 1] + dsk[p0 + 1] * bfhi(uw.x));
;                     const float y2 = gelu_tanh(acc[i][4 * k + 2] + dsk[p0 + 2] * bflo(uw.y)), y3 = gelu_tanh(acc[i][4 * k + 3] + dsk[p0 + 3] * bfhi(uw.y));
;                     v2u zw; zw.x = pk2(y0, y1); zw.y = pk2(y2, y3);
;                     *(GAS v2u*)((bf16*)(ws + WS_Z) + m * 512 + 16 * g + p0) = zw; }
	v_mov_b32_e32 v68, s46
	ds_read_b64 v[84:85], v68
	v_ashrrev_i32_e32 v83, 31, v82
	v_lshlrev_b64 v[88:89], 6, v[82:83]
	v_cmp_gt_i32_e32 vcc, s47, v82
	v_lshl_add_u64 v[102:103], v[88:89], 0, s[4:5]
	v_ashrrev_i32_e32 v83, 11, v102
	v_cndmask_b32_e32 v68, v94, v95, vcc
	v_lshl_add_u64 v[86:87], v[70:71], 0, v[68:69]
	v_ashrrev_i32_e32 v68, 6, v102
	v_add_u32_e32 v83, s30, v83
	v_mov_b32_e32 v96, s26
	v_cmp_gt_i32_e32 vcc, s47, v68
	s_lshl_b32 s28, s26, 4
	s_waitcnt lgkmcnt(0)
	v_readfirstlane_b32 s27, v84
	v_and_b32_e32 v97, 31, v68
	v_cndmask_b32_e32 v84, v96, v83, vcc
	s_ashr_i32 s29, s28, 31
	v_readfirstlane_b32 s31, v85
	v_or_b32_e32 v82, v97, v67
	v_ashrrev_i32_e32 v85, 31, v84
	v_lshlrev_b32_e32 v68, 6, v102
	s_lshl_b64 s[34:35], s[28:29], 2
	v_and_b32_e32 v68, 0xf80, v68
	v_ashrrev_i32_e32 v83, 31, v82
	v_lshlrev_b64 v[84:85], 16, v[84:85]
	v_lshl_add_u64 v[82:83], v[68:69], 0, v[82:83]
	v_lshl_add_u64 v[104:105], v[86:87], 0, v[84:85]
	s_add_u32 s26, s27, s34
	v_lshl_add_u64 v[82:83], v[82:83], 4, v[104:105]
	s_addc_u32 s27, s31, s35
	v_lshl_add_u64 v[98:99], v[188:189], 2, s[26:27]
	global_load_dwordx4 v[174:177], v[98:99], off
	global_load_dwordx4 v[178:181], v[98:99], off offset:32
	global_load_dwordx2 v[142:143], v[82:83], off
	global_load_dwordx2 v[144:145], v[82:83], off offset:512
	global_load_dwordx2 v[146:147], v[82:83], off offset:1024
	global_load_dwordx2 v[148:149], v[82:83], off offset:1536
	v_lshl_add_u64 v[82:83], v[82:83], 0, s[22:23]
	global_load_dwordx2 v[150:151], v[82:83], off
	global_load_dwordx2 v[152:153], v[82:83], off offset:512
	global_load_dwordx2 v[154:155], v[82:83], off offset:1024
	global_load_dwordx2 v[156:157], v[82:83], off offset:1536
	v_lshl_add_u64 v[82:83], v[82:83], 0, s[22:23]
	global_load_dwordx2 v[158:159], v[82:83], off
	global_load_dwordx2 v[160:161], v[82:83], off offset:512
	global_load_dwordx2 v[162:163], v[82:83], off offset:1024
	global_load_dwordx2 v[164:165], v[82:83], off offset:1536
	v_lshl_add_u64 v[82:83], v[82:83], 0, s[22:23]
	global_load_dwordx2 v[166:167], v[82:83], off
	global_load_dwordx2 v[168:169], v[82:83], off offset:512
	global_load_dwordx2 v[170:171], v[82:83], off offset:1024
	global_load_dwordx2 v[172:173], v[82:83], off offset:1536
	s_lshl_b64 s[26:27], s[28:29], 1
	s_add_u32 s26, s38, s26
	v_lshlrev_b64 v[102:103], 10, v[102:103]
	s_addc_u32 s27, s39, s27
	v_lshlrev_b64 v[84:85], 1, v[188:189]
	v_lshl_add_u64 v[102:103], s[26:27], 0, v[102:103]
	v_lshl_add_u64 v[102:103], v[102:103], 0, v[84:85]
	s_waitcnt vmcnt(15)
	v_lshlrev_b32_e32 v182, 16, v142
	v_and_b32_e32 v183, 0xffff0000, v142
	v_lshlrev_b32_e32 v184, 16, v143
	v_and_b32_e32 v185, 0xffff0000, v143
	v_fma_f32 v194, v174, v182, v50
	v_fma_f32 v195, v175, v183, v51
	v_fma_f32 v196, v176, v184, v52
	v_fma_f32 v197, v177, v185, v53
	v_mul_f32_e32 v190, 0x3d372713, v194
	v_mul_f32_e32 v191, 0x3d372713, v195
	v_mul_f32_e32 v192, 0x3d372713, v196
	v_mul_f32_e32 v193, 0x3d372713, v197
	v_mul_f32_e32 v190, v194, v190
	v_mul_f32_e32 v191, v195, v191
	v_mul_f32_e32 v192, v196, v192
	v_mul_f32_e32 v193, v197, v193
	v_fma_f32 v190, v194, v190, v194
	v_fma_f32 v191, v195, v191, v195
	v_fma_f32 v192, v196, v192, v196
	v_fma_f32 v193, v197, v193, v197
	v_mul_f32_e32 v190, 0x3f4c422a, v190
	v_mul_f32_e32 v191, 0x3f4c422a, v191
	v_mul_f32_e32 v192, 0x3f4c422a, v192
	v_mul_f32_e32 v193, 0x3f4c422a, v193
	v_mul_f32_e32 v190, 0xc038aa3b, v190
	v_mul_f32_e32 v191, 0xc038aa3b, v191
	v_mul_f32_e32 v192, 0xc038aa3b, v192
	v_mul_f32_e32 v193, 0xc038aa3b, v193
	v_exp_f32_e32 v190, v190
	v_exp_f32_e32 v191, v191
	v_exp_f32_e32 v192, v192
	v_exp_f32_e32 v193, v193
	v_add_f32_e32 v190, 1.0, v190
	v_add_f32_e32 v191, 1.0, v191
	v_add_f32_e32 v192, 1.0, v192
	v_add_f32_e32 v193, 1.0, v193
	v_rcp_f32_e32 v190, v190
	v_rcp_f32_e32 v191, v191
	v_rcp_f32_e32 v192, v192
	v_rcp_f32_e32 v193, v193
	v_mul_f32_e32 v194, v194, v190
	v_mul_f32_e32 v195, v195, v191
	v_mul_f32_e32 v196, v196, v192
	v_mul_f32_e32 v197, v197, v193
	v_cvt_pk_bf16_f32 v194, v194, v195
	v_cvt_pk_bf16_f32 v195, v196, v197
	global_store_dwordx2 v[102:103], v[194:195], off
	s_waitcnt vmcnt(15)
	v_lshlrev_b32_e32 v182, 16, v144
	v_and_b32_e32 v183, 0xffff0000, v144
	v_lshlrev_b32_e32 v184, 16, v145
	v_and_b32_e32 v185, 0xffff0000, v145
	v_fma_f32 v194, v178, v182, v54
	v_fma_f32 v195, v179, v183, v55
	v_fma_f32 v196, v180, v184, v56
	v_fma_f32 v197, v181, v185, v57
	v_mul_f32_e32 v190, 0x3d372713, v194
	v_mul_f32_e32 v191, 0x3d372713, v195
	v_mul_f32_e32 v192, 0x3d372713, v196
	v_mul_f32_e32 v193, 0x3d372713, v197
	v_mul_f32_e32 v190, v194, v190
	v_mul_f32_e32 v191, v195, v191
	v_mul_f32_e32 v192, v196, v192
	v_mul_f32_e32 v193, v197, v193
	v_fma_f32 v190, v194, v190, v194
	v_fma_f32 v191, v195, v191, v195
	v_fma_f32 v192, v196, v192, v196
	v_fma_f32 v193, v197, v193, v197
	v_mul_f32_e32 v190, 0x3f4c422a, v190
	v_mul_f32_e32 v191, 0x3f4c422a, v191
	v_mul_f32_e32 v192, 0x3f4c422a, v192
	v_mul_f32_e32 v193, 0x3f4c422a, v193
	v_mul_f32_e32 v190, 0xc038aa3b, v190
	v_mul_f32_e32 v191, 0xc038aa3b, v191
	v_mul_f32_e32 v192, 0xc038aa3b, v192
	v_mul_f32_e32 v193, 0xc038aa3b, v193
	v_exp_f32_e32 v190, v190
	v_exp_f32_e32 v191, v191
	v_exp_f32_e32 v192, v192
	v_exp_f32_e32 v193, v193
	v_add_f32_e32 v190, 1.0, v190
	v_add_f32_e32 v191, 1.0, v191
	v_add_f32_e32 v192, 1.0, v192
	v_add_f32_e32 v193, 1.0, v193
	v_rcp_f32_e32 v190, v190
	v_rcp_f32_e32 v191, v191
	v_rcp_f32_e32 v192, v192
	v_rcp_f32_e32 v193, v193
	v_mul_f32_e32 v194, v194, v190
	v_mul_f32_e32 v195, v195, v191
	v_mul_f32_e32 v196, v196, v192
	v_mul_f32_e32 v197, v197, v193
	v_cvt_pk_bf16_f32 v194, v194, v195
	v_cvt_pk_bf16_f32 v195, v196, v197
	global_store_dwordx2 v[102:103], v[194:195], off offset:16
	s_waitcnt vmcnt(15)
; #define GAS __attribute__((address_space(1)))
; __device__ __forceinline__ unsigned pk2(float lo, float hi) { const f32x2cv v = {lo, hi}; return __builtin_bit_cast(unsigned, __builtin_convertvector(v, bf16x2cv)); }
; __device__ __forceinline__ float gelu_tanh(float x) { const float u = 0.7978845608028654f * (x + 0.044715f * x * x * x); return x * __builtin_amdgcn_rcpf(1.0f + __builtin_amdgcn_exp2f(-2.8853900817779268f * u)); }
; __device__ __forceinline__ void ph_s5_out(Frame& F) {
;     ...
;                 for (int k = 0; k < 4; ++k) { const int tloc = 2 * (wave + 8 * i) + (k >> 1), p0 = 8 * (k & 1) + 4 * hh; const size_t m = (size_t)chunk * 64 + tloc;
;                     const v2u uw = *(const GAS v2u*)((chunk < 256 ? (const bf16*)(ws + WS_UG) : (const bf16*)(ws + WS_UGC)) + ug_index(g, (int)m, p0));
;                     const float y0 = gelu_tanh(acc[i][4 * k] + dsk[p0] * bflo(uw.x)), y1 = gelu_tanh(acc[i][4 * k + 1] + dsk[p0 + 1] * bfhi(uw.x));
;                     const float y2 = gelu_tanh(acc[i][4 * k + 2] + dsk[p0 + 2] * bflo(uw.y)), y3 = gelu_tanh(acc[i][4 * k + 3] + dsk[p0 + 3] * bfhi(uw.y));
;                     v2u zw; zw.x = pk2(y0, y1); zw.y = pk2(y2, y3);
;                     *(GAS v2u*)((bf16*)(ws + WS_Z) + m * 512 + 16 * g + p0) = zw; }
	v_lshlrev_b32_e32 v182, 16, v146
	v_and_b32_e32 v183, 0xffff0000, v146
	v_lshlrev_b32_e32 v184, 16, v147
	v_and_b32_e32 v185, 0xffff0000, v147
	v_fma_f32 v194, v174, v182, v58
	v_fma_f32 v195, v175, v183, v59
	v_fma_f32 v196, v176, v184, v60
	v_fma_f32 v197, v177, v185, v61
	v_mul_f32_e32 v190, 0x3d372713, v194
	v_mul_f32_e32 v191, 0x3d372713, v195
	v_mul_f32_e32 v192, 0x3d372713, v196
	v_mul_f32_e32 v193, 0x3d372713, v197
	v_mul_f32_e32 v190, v194, v190
	v_mul_f32_e32 v191, v195, v191
	v_mul_f32_e32 v192, v196, v192
	v_mul_f32_e32 v193, v197, v193
	v_fma_f32 v190, v194, v190, v194
	v_fma_f32 v191, v195, v191, v195
	v_fma_f32 v192, v196, v192, v196
	v_fma_f32 v193, v197, v193, v197
	v_mul_f32_e32 v190, 0x3f4c422a, v190
	v_mul_f32_e32 v191, 0x3f4c422a, v191
	v_mul_f32_e32 v192, 0x3f4c422a, v192
	v_mul_f32_e32 v193, 0x3f4c422a, v193
	v_mul_f32_e32 v190, 0xc038aa3b, v190
	v_mul_f32_e32 v191, 0xc038aa3b, v191
	v_mul_f32_e32 v192, 0xc038aa3b, v192
	v_mul_f32_e32 v193, 0xc038aa3b, v193
	v_exp_f32_e32 v190, v190
	v_exp_f32_e32 v191, v191
	v_exp_f32_e32 v192, v192
	v_exp_f32_e32 v193, v193
	v_add_f32_e32 v190, 1.0, v190
	v_add_f32_e32 v191, 1.0, v191
	v_add_f32_e32 v192, 1.0, v192
	v_add_f32_e32 v193, 1.0, v193
	v_rcp_f32_e32 v190, v190
	v_rcp_f32_e32 v191, v191
	v_rcp_f32_e32 v192, v192
	v_rcp_f32_e32 v193, v193
	v_mul_f32_e32 v194, v194, v190
	v_mul_f32_e32 v195, v195, v191
	v_mul_f32_e32 v196, v196, v192
	v_mul_f32_e32 v197, v197, v193
	v_cvt_pk_bf16_f32 v194, v194, v195
	v_cvt_pk_bf16_f32 v195, v196, v197
	global_store_dwordx2 v[102:103], v[194:195], off offset:1024
	s_waitcnt vmcnt(15)
	v_lshlrev_b32_e32 v182, 16, v148
	v_and_b32_e32 v183, 0xffff0000, v148
	v_lshlrev_b32_e32 v184, 16, v149
	v_and_b32_e32 v185, 0xffff0000, v149
	v_fma_f32 v194, v178, v182, v62
	v_fma_f32 v195, v179, v183, v63
	v_fma_f32 v196, v180, v184, v64
	v_fma_f32 v197, v181, v185, v65
	v_mul_f32_e32 v190, 0x3d372713, v194
	v_mul_f32_e32 v191, 0x3d372713, v195
	v_mul_f32_e32 v192, 0x3d372713, v196
	v_mul_f32_e32 v193, 0x3d372713, v197
	v_mul_f32_e32 v190, v194, v190
	v_mul_f32_e32 v191, v195, v191
	v_mul_f32_e32 v192, v196, v192
	v_mul_f32_e32 v193, v197, v193
	v_fma_f32 v190, v194, v190, v194
	v_fma_f32 v191, v195, v191, v195
	v_fma_f32 v192, v196, v192, v196
	v_fma_f32 v193, v197, v193, v197
	v_mul_f32_e32 v190, 0x3f4c422a, v190
	v_mul_f32_e32 v191, 0x3f4c422a, v191
	v_mul_f32_e32 v192, 0x3f4c422a, v192
	v_mul_f32_e32 v193, 0x3f4c422a, v193
	v_mul_f32_e32 v190, 0xc038aa3b, v190
	v_mul_f32_e32 v191, 0xc038aa3b, v191
	v_mul_f32_e32 v192, 0xc038aa3b, v192
	v_mul_f32_e32 v193, 0xc038aa3b, v193
	v_exp_f32_e32 v190, v190
	v_exp_f32_e32 v191, v191
	v_exp_f32_e32 v192, v192
	v_exp_f32_e32 v193, v193
	v_add_f32_e32 v190, 1.0, v190
	v_add_f32_e32 v191, 1.0, v191
	v_add_f32_e32 v192, 1.0, v192
	v_add_f32_e32 v193, 1.0, v193
	v_rcp_f32_e32 v190, v190
	v_rcp_f32_e32 v191, v191
	v_rcp_f32_e32 v192, v192
	v_rcp_f32_e32 v193, v193
	v_mul_f32_e32 v194, v194, v190
	v_mul_f32_e32 v195, v195, v191
	v_mul_f32_e32 v196, v196, v192
	v_mul_f32_e32 v197, v197, v193
	v_cvt_pk_bf16_f32 v194, v194, v195
	v_cvt_pk_bf16_f32 v195, v196, v197
	global_store_dwordx2 v[102:103], v[194:195], off offset:1040
	v_lshl_add_u64 v[102:103], v[102:103], 0, s[22:23]
	s_waitcnt vmcnt(15)
	v_lshlrev_b32_e32 v182, 16, v150
	v_and_b32_e32 v183, 0xffff0000, v150
	v_lshlrev_b32_e32 v184, 16, v151
	v_and_b32_e32 v185, 0xffff0000, v151
	v_fma_f32 v194, v174, v182, v34
	v_fma_f32 v195, v175, v183, v35
	v_fma_f32 v196, v176, v184, v36
	v_fma_f32 v197, v177, v185, v37
	v_mul_f32_e32 v190, 0x3d372713, v194
	v_mul_f32_e32 v191, 0x3d372713, v195
	v_mul_f32_e32 v192, 0x3d372713, v196
	v_mul_f32_e32 v193, 0x3d372713, v197
	v_mul_f32_e32 v190, v194, v190
	v_mul_f32_e32 v191, v195, v191
	v_mul_f32_e32 v192, v196, v192
	v_mul_f32_e32 v193, v197, v193
	v_fma_f32 v190, v194, v190, v194
	v_fma_f32 v191, v195, v191, v195
	v_fma_f32 v192, v196, v192, v196
	v_fma_f32 v193, v197, v193, v197
	v_mul_f32_e32 v190, 0x3f4c422a, v190
	v_mul_f32_e32 v191, 0x3f4c422a, v191
	v_mul_f32_e32 v192, 0x3f4c422a, v192
	v_mul_f32_e32 v193, 0x3f4c422a, v193
	v_mul_f32_e32 v190, 0xc038aa3b, v190
	v_mul_f32_e32 v191, 0xc038aa3b, v191
	v_mul_f32_e32 v192, 0xc038aa3b, v192
	v_mul_f32_e32 v193, 0xc038aa3b, v193
	v_exp_f32_e32 v190, v190
	v_exp_f32_e32 v191, v191
	v_exp_f32_e32 v192, v192
	v_exp_f32_e32 v193, v193
	v_add_f32_e32 v190, 1.0, v190
	v_add_f32_e32 v191, 1.0, v191
	v_add_f32_e32 v192, 1.0, v192
	v_add_f32_e32 v193, 1.0, v193
	v_rcp_f32_e32 v190, v190
	v_rcp_f32_e32 v191, v191
	v_rcp_f32_e32 v192, v192
	v_rcp_f32_e32 v193, v193
	v_mul_f32_e32 v194, v194, v190
	v_mul_f32_e32 v195, v195, v191
	v_mul_f32_e32 v196, v196, v192
	v_mul_f32_e32 v197, v197, v193
	v_cvt_pk_bf16_f32 v194, v194, v195
	v_cvt_pk_bf16_f32 v195, v196, v197
	global_store_dwordx2 v[102:103], v[194:195], off
	s_waitcnt vmcnt(15)
; #define GAS __attribute__((address_space(1)))
; __device__ __forceinline__ unsigned pk2(float lo, float hi) { const f32x2cv v = {lo, hi}; return __builtin_bit_cast(unsigned, __builtin_convertvector(v, bf16x2cv)); }
; __device__ __forceinline__ float gelu_tanh(float x) { const float u = 0.7978845608028654f * (x + 0.044715f * x * x * x); return x * __builtin_amdgcn_rcpf(1.0f + __builtin_amdgcn_exp2f(-2.8853900817779268f * u)); }
; __device__ __forceinline__ void ph_s5_out(Frame& F) {
;     ...
;                 for (int k = 0; k < 4; ++k) { const int tloc = 2 * (wave + 8 * i) + (k >> 1), p0 = 8 * (k & 1) + 4 * hh; const size_t m = (size_t)chunk * 64 + tloc;
;                     const v2u uw = *(const GAS v2u*)((chunk < 256 ? (const bf16*)(ws + WS_UG) : (const bf16*)(ws + WS_UGC)) + ug_index(g, (int)m, p0));
;                     const float y0 = gelu_tanh(acc[i][4 * k] + dsk[p0] * bflo(uw.x)), y1 = gelu_tanh(acc[i][4 * k + 1] + dsk[p0 + 1] * bfhi(uw.x));
;                     const float y2 = gelu_tanh(acc[i][4 * k + 2] + dsk[p0 + 2] * bflo(uw.y)), y3 = gelu_tanh(acc[i][4 * k + 3] + dsk[p0 + 3] * bfhi(uw.y));
;                     v2u zw; zw.x = pk2(y0, y1); zw.y = pk2(y2, y3);
;                     *(GAS v2u*)((bf16*)(ws + WS_Z) + m * 512 + 16 * g + p0) = zw; }
	v_lshlrev_b32_e32 v182, 16, v152
	v_and_b32_e32 v183, 0xffff0000, v152
	v_lshlrev_b32_e32 v184, 16, v153
	v_and_b32_e32 v185, 0xffff0000, v153
	v_fma_f32 v194, v178, v182, v38
	v_fma_f32 v195, v179, v183, v39
	v_fma_f32 v196, v180, v184, v40
	v_fma_f32 v197, v181, v185, v41
	v_mul_f32_e32 v190, 0x3d372713, v194
	v_mul_f32_e32 v191, 0x3d372713, v195
	v_mul_f32_e32 v192, 0x3d372713, v196
	v_mul_f32_e32 v193, 0x3d372713, v197
	v_mul_f32_e32 v190, v194, v190
	v_mul_f32_e32 v191, v195, v191
	v_mul_f32_e32 v192, v196, v192
	v_mul_f32_e32 v193, v197, v193
	v_fma_f32 v190, v194, v190, v194
	v_fma_f32 v191, v195, v191, v195
	v_fma_f32 v192, v196, v192, v196
	v_fma_f32 v193, v197, v193, v197
	v_mul_f32_e32 v190, 0x3f4c422a, v190
	v_mul_f32_e32 v191, 0x3f4c422a, v191
	v_mul_f32_e32 v192, 0x3f4c422a, v192
	v_mul_f32_e32 v193, 0x3f4c422a, v193
	v_mul_f32_e32 v190, 0xc038aa3b, v190
	v_mul_f32_e32 v191, 0xc038aa3b, v191
	v_mul_f32_e32 v192, 0xc038aa3b, v192
	v_mul_f32_e32 v193, 0xc038aa3b, v193
	v_exp_f32_e32 v190, v190
	v_exp_f32_e32 v191, v191
	v_exp_f32_e32 v192, v192
	v_exp_f32_e32 v193, v193
	v_add_f32_e32 v190, 1.0, v190
	v_add_f32_e32 v191, 1.0, v191
	v_add_f32_e32 v192, 1.0, v192
	v_add_f32_e32 v193, 1.0, v193
	v_rcp_f32_e32 v190, v190
	v_rcp_f32_e32 v191, v191
	v_rcp_f32_e32 v192, v192
	v_rcp_f32_e32 v193, v193
	v_mul_f32_e32 v194, v194, v190
	v_mul_f32_e32 v195, v195, v191
	v_mul_f32_e32 v196, v196, v192
	v_mul_f32_e32 v197, v197, v193
	v_cvt_pk_bf16_f32 v194, v194, v195
	v_cvt_pk_bf16_f32 v195, v196, v197
	global_store_dwordx2 v[102:103], v[194:195], off offset:16
	s_waitcnt vmcnt(15)
	v_lshlrev_b32_e32 v182, 16, v154
	v_and_b32_e32 v183, 0xffff0000, v154
	v_lshlrev_b32_e32 v184, 16, v155
	v_and_b32_e32 v185, 0xffff0000, v155
	v_fma_f32 v194, v174, v182, v42
	v_fma_f32 v195, v175, v183, v43
	v_fma_f32 v196, v176, v184, v44
	v_fma_f32 v197, v177, v185, v45
	v_mul_f32_e32 v190, 0x3d372713, v194
	v_mul_f32_e32 v191, 0x3d372713, v195
	v_mul_f32_e32 v192, 0x3d372713, v196
	v_mul_f32_e32 v193, 0x3d372713, v197
	v_mul_f32_e32 v190, v194, v190
	v_mul_f32_e32 v191, v195, v191
	v_mul_f32_e32 v192, v196, v192
	v_mul_f32_e32 v193, v197, v193
	v_fma_f32 v190, v194, v190, v194
	v_fma_f32 v191, v195, v191, v195
	v_fma_f32 v192, v196, v192, v196
	v_fma_f32 v193, v197, v193, v197
	v_mul_f32_e32 v190, 0x3f4c422a, v190
	v_mul_f32_e32 v191, 0x3f4c422a, v191
	v_mul_f32_e32 v192, 0x3f4c422a, v192
	v_mul_f32_e32 v193, 0x3f4c422a, v193
	v_mul_f32_e32 v190, 0xc038aa3b, v190
	v_mul_f32_e32 v191, 0xc038aa3b, v191
	v_mul_f32_e32 v192, 0xc038aa3b, v192
	v_mul_f32_e32 v193, 0xc038aa3b, v193
	v_exp_f32_e32 v190, v190
	v_exp_f32_e32 v191, v191
	v_exp_f32_e32 v192, v192
	v_exp_f32_e32 v193, v193
	v_add_f32_e32 v190, 1.0, v190
	v_add_f32_e32 v191, 1.0, v191
	v_add_f32_e32 v192, 1.0, v192
	v_add_f32_e32 v193, 1.0, v193
	v_rcp_f32_e32 v190, v190
	v_rcp_f32_e32 v191, v191
	v_rcp_f32_e32 v192, v192
	v_rcp_f32_e32 v193, v193
	v_mul_f32_e32 v194, v194, v190
	v_mul_f32_e32 v195, v195, v191
	v_mul_f32_e32 v196, v196, v192
	v_mul_f32_e32 v197, v197, v193
	v_cvt_pk_bf16_f32 v194, v194, v195
	v_cvt_pk_bf16_f32 v195, v196, v197
	global_store_dwordx2 v[102:103], v[194:195], off offset:1024
	s_waitcnt vmcnt(15)
	v_lshlrev_b32_e32 v182, 16, v156
	v_and_b32_e32 v183, 0xffff0000, v156
	v_lshlrev_b32_e32 v184, 16, v157
	v_and_b32_e32 v185, 0xffff0000, v157
	v_fma_f32 v194, v178, v182, v46
	v_fma_f32 v195, v179, v183, v47
	v_fma_f32 v196, v180, v184, v48
	v_fma_f32 v197, v181, v185, v49
	v_mul_f32_e32 v190, 0x3d372713, v194
	v_mul_f32_e32 v191, 0x3d372713, v195
	v_mul_f32_e32 v192, 0x3d372713, v196
	v_mul_f32_e32 v193, 0x3d372713, v197
	v_mul_f32_e32 v190, v194, v190
	v_mul_f32_e32 v191, v195, v191
	v_mul_f32_e32 v192, v196, v192
	v_mul_f32_e32 v193, v197, v193
	v_fma_f32 v190, v194, v190, v194
	v_fma_f32 v191, v195, v191, v195
	v_fma_f32 v192, v196, v192, v196
	v_fma_f32 v193, v197, v193, v197
	v_mul_f32_e32 v190, 0x3f4c422a, v190
	v_mul_f32_e32 v191, 0x3f4c422a, v191
	v_mul_f32_e32 v192, 0x3f4c422a, v192
	v_mul_f32_e32 v193, 0x3f4c422a, v193
	v_mul_f32_e32 v190, 0xc038aa3b, v190
	v_mul_f32_e32 v191, 0xc038aa3b, v191
	v_mul_f32_e32 v192, 0xc038aa3b, v192
	v_mul_f32_e32 v193, 0xc038aa3b, v193
	v_exp_f32_e32 v190, v190
	v_exp_f32_e32 v191, v191
	v_exp_f32_e32 v192, v192
	v_exp_f32_e32 v193, v193
	v_add_f32_e32 v190, 1.0, v190
	v_add_f32_e32 v191, 1.0, v191
	v_add_f32_e32 v192, 1.0, v192
	v_add_f32_e32 v193, 1.0, v193
	v_rcp_f32_e32 v190, v190
	v_rcp_f32_e32 v191, v191
	v_rcp_f32_e32 v192, v192
	v_rcp_f32_e32 v193, v193
	v_mul_f32_e32 v194, v194, v190
	v_mul_f32_e32 v195, v195, v191
	v_mul_f32_e32 v196, v196, v192
	v_mul_f32_e32 v197, v197, v193
	v_cvt_pk_bf16_f32 v194, v194, v195
	v_cvt_pk_bf16_f32 v195, v196, v197
	global_store_dwordx2 v[102:103], v[194:195], off offset:1040
	v_lshl_add_u64 v[102:103], v[102:103], 0, s[22:23]
	s_waitcnt vmcnt(15)
; #define GAS __attribute__((address_space(1)))
; __device__ __forceinline__ unsigned pk2(float lo, float hi) { const f32x2cv v = {lo, hi}; return __builtin_bit_cast(unsigned, __builtin_convertvector(v, bf16x2cv)); }
; __device__ __forceinline__ float gelu_tanh(float x) { const float u = 0.7978845608028654f * (x + 0.044715f * x * x * x); return x * __builtin_amdgcn_rcpf(1.0f + __builtin_amdgcn_exp2f(-2.8853900817779268f * u)); }
; __device__ __forceinline__ void ph_s5_out(Frame& F) {
;     ...
;                 for (int k = 0; k < 4; ++k) { const int tloc = 2 * (wave + 8 * i) + (k >> 1), p0 = 8 * (k & 1) + 4 * hh; const size_t m = (size_t)chunk * 64 + tloc;
;                     const v2u uw = *(const GAS v2u*)((chunk < 256 ? (const bf16*)(ws + WS_UG) : (const bf16*)(ws + WS_UGC)) + ug_index(g, (int)m, p0));
;                     const float y0 = gelu_tanh(acc[i][4 * k] + dsk[p0] * bflo(uw.x)), y1 = gelu_tanh(acc[i][4 * k + 1] + dsk[p0 + 1] * bfhi(uw.x));
;                     const float y2 = gelu_tanh(acc[i][4 * k + 2] + dsk[p0 + 2] * bflo(uw.y)), y3 = gelu_tanh(acc[i][4 * k + 3] + dsk[p0 + 3] * bfhi(uw.y));
;                     v2u zw; zw.x = pk2(y0, y1); zw.y = pk2(y2, y3);
;                     *(GAS v2u*)((bf16*)(ws + WS_Z) + m * 512 + 16 * g + p0) = zw; }
	v_lshlrev_b32_e32 v182, 16, v158
	v_and_b32_e32 v183, 0xffff0000, v158
	v_lshlrev_b32_e32 v184, 16, v159
	v_and_b32_e32 v185, 0xffff0000, v159
	v_fma_f32 v194, v174, v182, v18
	v_fma_f32 v195, v175, v183, v19
	v_fma_f32 v196, v176, v184, v20
	v_fma_f32 v197, v177, v185, v21
	v_mul_f32_e32 v190, 0x3d372713, v194
	v_mul_f32_e32 v191, 0x3d372713, v195
	v_mul_f32_e32 v192, 0x3d372713, v196
	v_mul_f32_e32 v193, 0x3d372713, v197
	v_mul_f32_e32 v190, v194, v190
	v_mul_f32_e32 v191, v195, v191
	v_mul_f32_e32 v192, v196, v192
	v_mul_f32_e32 v193, v197, v193
	v_fma_f32 v190, v194, v190, v194
	v_fma_f32 v191, v195, v191, v195
	v_fma_f32 v192, v196, v192, v196
	v_fma_f32 v193, v197, v193, v197
	v_mul_f32_e32 v190, 0x3f4c422a, v190
	v_mul_f32_e32 v191, 0x3f4c422a, v191
	v_mul_f32_e32 v192, 0x3f4c422a, v192
	v_mul_f32_e32 v193, 0x3f4c422a, v193
	v_mul_f32_e32 v190, 0xc038aa3b, v190
	v_mul_f32_e32 v191, 0xc038aa3b, v191
	v_mul_f32_e32 v192, 0xc038aa3b, v192
	v_mul_f32_e32 v193, 0xc038aa3b, v193
	v_exp_f32_e32 v190, v190
	v_exp_f32_e32 v191, v191
	v_exp_f32_e32 v192, v192
	v_exp_f32_e32 v193, v193
	v_add_f32_e32 v190, 1.0, v190
	v_add_f32_e32 v191, 1.0, v191
	v_add_f32_e32 v192, 1.0, v192
	v_add_f32_e32 v193, 1.0, v193
	v_rcp_f32_e32 v190, v190
	v_rcp_f32_e32 v191, v191
	v_rcp_f32_e32 v192, v192
	v_rcp_f32_e32 v193, v193
	v_mul_f32_e32 v194, v194, v190
	v_mul_f32_e32 v195, v195, v191
	v_mul_f32_e32 v196, v196, v192
	v_mul_f32_e32 v197, v197, v193
	v_cvt_pk_bf16_f32 v194, v194, v195
	v_cvt_pk_bf16_f32 v195, v196, v197
	global_store_dwordx2 v[102:103], v[194:195], off
	s_waitcnt vmcnt(15)
	v_lshlrev_b32_e32 v182, 16, v160
	v_and_b32_e32 v183, 0xffff0000, v160
	v_lshlrev_b32_e32 v184, 16, v161
	v_and_b32_e32 v185, 0xffff0000, v161
	v_fma_f32 v194, v178, v182, v22
	v_fma_f32 v195, v179, v183, v23
	v_fma_f32 v196, v180, v184, v24
	v_fma_f32 v197, v181, v185, v25
	v_mul_f32_e32 v190, 0x3d372713, v194
	v_mul_f32_e32 v191, 0x3d372713, v195
	v_mul_f32_e32 v192, 0x3d372713, v196
	v_mul_f32_e32 v193, 0x3d372713, v197
	v_mul_f32_e32 v190, v194, v190
	v_mul_f32_e32 v191, v195, v191
	v_mul_f32_e32 v192, v196, v192
	v_mul_f32_e32 v193, v197, v193
	v_fma_f32 v190, v194, v190, v194
	v_fma_f32 v191, v195, v191, v195
	v_fma_f32 v192, v196, v192, v196
	v_fma_f32 v193, v197, v193, v197
	v_mul_f32_e32 v190, 0x3f4c422a, v190
	v_mul_f32_e32 v191, 0x3f4c422a, v191
	v_mul_f32_e32 v192, 0x3f4c422a, v192
	v_mul_f32_e32 v193, 0x3f4c422a, v193
	v_mul_f32_e32 v190, 0xc038aa3b, v190
	v_mul_f32_e32 v191, 0xc038aa3b, v191
	v_mul_f32_e32 v192, 0xc038aa3b, v192
	v_mul_f32_e32 v193, 0xc038aa3b, v193
	v_exp_f32_e32 v190, v190
	v_exp_f32_e32 v191, v191
	v_exp_f32_e32 v192, v192
	v_exp_f32_e32 v193, v193
	v_add_f32_e32 v190, 1.0, v190
	v_add_f32_e32 v191, 1.0, v191
	v_add_f32_e32 v192, 1.0, v192
	v_add_f32_e32 v193, 1.0, v193
	v_rcp_f32_e32 v190, v190
	v_rcp_f32_e32 v191, v191
	v_rcp_f32_e32 v192, v192
	v_rcp_f32_e32 v193, v193
	v_mul_f32_e32 v194, v194, v190
	v_mul_f32_e32 v195, v195, v191
	v_mul_f32_e32 v196, v196, v192
	v_mul_f32_e32 v197, v197, v193
	v_cvt_pk_bf16_f32 v194, v194, v195
	v_cvt_pk_bf16_f32 v195, v196, v197
	global_store_dwordx2 v[102:103], v[194:195], off offset:16
	s_waitcnt vmcnt(15)
	v_lshlrev_b32_e32 v182, 16, v162
	v_and_b32_e32 v183, 0xffff0000, v162
	v_lshlrev_b32_e32 v184, 16, v163
	v_and_b32_e32 v185, 0xffff0000, v163
	v_fma_f32 v194, v174, v182, v26
	v_fma_f32 v195, v175, v183, v27
	v_fma_f32 v196, v176, v184, v28
	v_fma_f32 v197, v177, v185, v29
	v_mul_f32_e32 v190, 0x3d372713, v194
	v_mul_f32_e32 v191, 0x3d372713, v195
	v_mul_f32_e32 v192, 0x3d372713, v196
	v_mul_f32_e32 v193, 0x3d372713, v197
	v_mul_f32_e32 v190, v194, v190
	v_mul_f32_e32 v191, v195, v191
	v_mul_f32_e32 v192, v196, v192
	v_mul_f32_e32 v193, v197, v193
	v_fma_f32 v190, v194, v190, v194
	v_fma_f32 v191, v195, v191, v195
	v_fma_f32 v192, v196, v192, v196
	v_fma_f32 v193, v197, v193, v197
	v_mul_f32_e32 v190, 0x3f4c422a, v190
	v_mul_f32_e32 v191, 0x3f4c422a, v191
	v_mul_f32_e32 v192, 0x3f4c422a, v192
	v_mul_f32_e32 v193, 0x3f4c422a, v193
	v_mul_f32_e32 v190, 0xc038aa3b, v190
	v_mul_f32_e32 v191, 0xc038aa3b, v191
	v_mul_f32_e32 v192, 0xc038aa3b, v192
	v_mul_f32_e32 v193, 0xc038aa3b, v193
	v_exp_f32_e32 v190, v190
	v_exp_f32_e32 v191, v191
	v_exp_f32_e32 v192, v192
	v_exp_f32_e32 v193, v193
	v_add_f32_e32 v190, 1.0, v190
	v_add_f32_e32 v191, 1.0, v191
	v_add_f32_e32 v192, 1.0, v192
	v_add_f32_e32 v193, 1.0, v193
	v_rcp_f32_e32 v190, v190
	v_rcp_f32_e32 v191, v191
	v_rcp_f32_e32 v192, v192
	v_rcp_f32_e32 v193, v193
	v_mul_f32_e32 v194, v194, v190
	v_mul_f32_e32 v195, v195, v191
	v_mul_f32_e32 v196, v196, v192
	v_mul_f32_e32 v197, v197, v193
	v_cvt_pk_bf16_f32 v194, v194, v195
	v_cvt_pk_bf16_f32 v195, v196, v197
	global_store_dwordx2 v[102:103], v[194:195], off offset:1024
	s_waitcnt vmcnt(15)
; #define GAS __attribute__((address_space(1)))
; __device__ __forceinline__ unsigned pk2(float lo, float hi) { const f32x2cv v = {lo, hi}; return __builtin_bit_cast(unsigned, __builtin_convertvector(v, bf16x2cv)); }
; __device__ __forceinline__ float gelu_tanh(float x) { const float u = 0.7978845608028654f * (x + 0.044715f * x * x * x); return x * __builtin_amdgcn_rcpf(1.0f + __builtin_amdgcn_exp2f(-2.8853900817779268f * u)); }
; __device__ __forceinline__ void ph_s5_out(Frame& F) {
;     ...
;                 for (int k = 0; k < 4; ++k) { const int tloc = 2 * (wave + 8 * i) + (k >> 1), p0 = 8 * (k & 1) + 4 * hh; const size_t m = (size_t)chunk * 64 + tloc;
;                     const v2u uw = *(const GAS v2u*)((chunk < 256 ? (const bf16*)(ws + WS_UG) : (const bf16*)(ws + WS_UGC)) + ug_index(g, (int)m, p0));
;                     const float y0 = gelu_tanh(acc[i][4 * k] + dsk[p0] * bflo(uw.x)), y1 = gelu_tanh(acc[i][4 * k + 1] + dsk[p0 + 1] * bfhi(uw.x));
;                     const float y2 = gelu_tanh(acc[i][4 * k + 2] + dsk[p0 + 2] * bflo(uw.y)), y3 = gelu_tanh(acc[i][4 * k + 3] + dsk[p0 + 3] * bfhi(uw.y));
;                     v2u zw; zw.x = pk2(y0, y1); zw.y = pk2(y2, y3);
;                     *(GAS v2u*)((bf16*)(ws + WS_Z) + m * 512 + 16 * g + p0) = zw; }
	v_lshlrev_b32_e32 v182, 16, v164
	v_and_b32_e32 v183, 0xffff0000, v164
	v_lshlrev_b32_e32 v184, 16, v165
	v_and_b32_e32 v185, 0xffff0000, v165
	v_fma_f32 v194, v178, v182, v30
	v_fma_f32 v195, v179, v183, v31
	v_fma_f32 v196, v180, v184, v32
	v_fma_f32 v197, v181, v185, v33
	v_mul_f32_e32 v190, 0x3d372713, v194
	v_mul_f32_e32 v191, 0x3d372713, v195
	v_mul_f32_e32 v192, 0x3d372713, v196
	v_mul_f32_e32 v193, 0x3d372713, v197
	v_mul_f32_e32 v190, v194, v190
	v_mul_f32_e32 v191, v195, v191
	v_mul_f32_e32 v192, v196, v192
	v_mul_f32_e32 v193, v197, v193
	v_fma_f32 v190, v194, v190, v194
	v_fma_f32 v191, v195, v191, v195
	v_fma_f32 v192, v196, v192, v196
	v_fma_f32 v193, v197, v193, v197
	v_mul_f32_e32 v190, 0x3f4c422a, v190
	v_mul_f32_e32 v191, 0x3f4c422a, v191
	v_mul_f32_e32 v192, 0x3f4c422a, v192
	v_mul_f32_e32 v193, 0x3f4c422a, v193
	v_mul_f32_e32 v190, 0xc038aa3b, v190
	v_mul_f32_e32 v191, 0xc038aa3b, v191
	v_mul_f32_e32 v192, 0xc038aa3b, v192
	v_mul_f32_e32 v193, 0xc038aa3b, v193
	v_exp_f32_e32 v190, v190
	v_exp_f32_e32 v191, v191
	v_exp_f32_e32 v192, v192
	v_exp_f32_e32 v193, v193
	v_add_f32_e32 v190, 1.0, v190
	v_add_f32_e32 v191, 1.0, v191
	v_add_f32_e32 v192, 1.0, v192
	v_add_f32_e32 v193, 1.0, v193
	v_rcp_f32_e32 v190, v190
	v_rcp_f32_e32 v191, v191
	v_rcp_f32_e32 v192, v192
	v_rcp_f32_e32 v193, v193
	v_mul_f32_e32 v194, v194, v190
	v_mul_f32_e32 v195, v195, v191
	v_mul_f32_e32 v196, v196, v192
	v_mul_f32_e32 v197, v197, v193
	v_cvt_pk_bf16_f32 v194, v194, v195
	v_cvt_pk_bf16_f32 v195, v196, v197
	global_store_dwordx2 v[102:103], v[194:195], off offset:1040
	v_lshl_add_u64 v[102:103], v[102:103], 0, s[22:23]
	s_waitcnt vmcnt(15)
	v_lshlrev_b32_e32 v182, 16, v166
	v_and_b32_e32 v183, 0xffff0000, v166
	v_lshlrev_b32_e32 v184, 16, v167
	v_and_b32_e32 v185, 0xffff0000, v167
	v_fma_f32 v194, v174, v182, v2
	v_fma_f32 v195, v175, v183, v3
	v_fma_f32 v196, v176, v184, v4
	v_fma_f32 v197, v177, v185, v5
	v_mul_f32_e32 v190, 0x3d372713, v194
	v_mul_f32_e32 v191, 0x3d372713, v195
	v_mul_f32_e32 v192, 0x3d372713, v196
	v_mul_f32_e32 v193, 0x3d372713, v197
	v_mul_f32_e32 v190, v194, v190
	v_mul_f32_e32 v191, v195, v191
	v_mul_f32_e32 v192, v196, v192
	v_mul_f32_e32 v193, v197, v193
	v_fma_f32 v190, v194, v190, v194
	v_fma_f32 v191, v195, v191, v195
	v_fma_f32 v192, v196, v192, v196
	v_fma_f32 v193, v197, v193, v197
	v_mul_f32_e32 v190, 0x3f4c422a, v190
	v_mul_f32_e32 v191, 0x3f4c422a, v191
	v_mul_f32_e32 v192, 0x3f4c422a, v192
	v_mul_f32_e32 v193, 0x3f4c422a, v193
	v_mul_f32_e32 v190, 0xc038aa3b, v190
	v_mul_f32_e32 v191, 0xc038aa3b, v191
	v_mul_f32_e32 v192, 0xc038aa3b, v192
	v_mul_f32_e32 v193, 0xc038aa3b, v193
	v_exp_f32_e32 v190, v190
	v_exp_f32_e32 v191, v191
	v_exp_f32_e32 v192, v192
	v_exp_f32_e32 v193, v193
	v_add_f32_e32 v190, 1.0, v190
	v_add_f32_e32 v191, 1.0, v191
	v_add_f32_e32 v192, 1.0, v192
	v_add_f32_e32 v193, 1.0, v193
	v_rcp_f32_e32 v190, v190
	v_rcp_f32_e32 v191, v191
	v_rcp_f32_e32 v192, v192
	v_rcp_f32_e32 v193, v193
	v_mul_f32_e32 v194, v194, v190
	v_mul_f32_e32 v195, v195, v191
	v_mul_f32_e32 v196, v196, v192
	v_mul_f32_e32 v197, v197, v193
	v_cvt_pk_bf16_f32 v194, v194, v195
	v_cvt_pk_bf16_f32 v195, v196, v197
	global_store_dwordx2 v[102:103], v[194:195], off
	s_waitcnt vmcnt(15)
; #define GAS __attribute__((address_space(1)))
; __device__ __forceinline__ unsigned pk2(float lo, float hi) { const f32x2cv v = {lo, hi}; return __builtin_bit_cast(unsigned, __builtin_convertvector(v, bf16x2cv)); }
; __device__ __forceinline__ float gelu_tanh(float x) { const float u = 0.7978845608028654f * (x + 0.044715f * x * x * x); return x * __builtin_amdgcn_rcpf(1.0f + __builtin_amdgcn_exp2f(-2.8853900817779268f * u)); }
; __device__ __forceinline__ void ph_s5_out(Frame& F) {
;     ...
;                 for (int k = 0; k < 4; ++k) { const int tloc = 2 * (wave + 8 * i) + (k >> 1), p0 = 8 * (k & 1) + 4 * hh; const size_t m = (size_t)chunk * 64 + tloc;
;                     const v2u uw = *(const GAS v2u*)((chunk < 256 ? (const bf16*)(ws + WS_UG) : (const bf16*)(ws + WS_UGC)) + ug_index(g, (int)m, p0));
;                     const float y0 = gelu_tanh(acc[i][4 * k] + dsk[p0] * bflo(uw.x)), y1 = gelu_tanh(acc[i][4 * k + 1] + dsk[p0 + 1] * bfhi(uw.x));
;                     const float y2 = gelu_tanh(acc[i][4 * k + 2] + dsk[p0 + 2] * bflo(uw.y)), y3 = gelu_tanh(acc[i][4 * k + 3] + dsk[p0 + 3] * bfhi(uw.y));
;                     v2u zw; zw.x = pk2(y0, y1); zw.y = pk2(y2, y3);
;                     *(GAS v2u*)((bf16*)(ws + WS_Z) + m * 512 + 16 * g + p0) = zw; }
	v_lshlrev_b32_e32 v182, 16, v168
	v_and_b32_e32 v183, 0xffff0000, v168
	v_lshlrev_b32_e32 v184, 16, v169
	v_and_b32_e32 v185, 0xffff0000, v169
	v_fma_f32 v194, v178, v182, v6
	v_fma_f32 v195, v179, v183, v7
	v_fma_f32 v196, v180, v184, v8
	v_fma_f32 v197, v181, v185, v9
	v_mul_f32_e32 v190, 0x3d372713, v194
	v_mul_f32_e32 v191, 0x3d372713, v195
	v_mul_f32_e32 v192, 0x3d372713, v196
	v_mul_f32_e32 v193, 0x3d372713, v197
	v_mul_f32_e32 v190, v194, v190
	v_mul_f32_e32 v191, v195, v191
	v_mul_f32_e32 v192, v196, v192
	v_mul_f32_e32 v193, v197, v193
	v_fma_f32 v190, v194, v190, v194
	v_fma_f32 v191, v195, v191, v195
	v_fma_f32 v192, v196, v192, v196
	v_fma_f32 v193, v197, v193, v197
	v_mul_f32_e32 v190, 0x3f4c422a, v190
	v_mul_f32_e32 v191, 0x3f4c422a, v191
	v_mul_f32_e32 v192, 0x3f4c422a, v192
	v_mul_f32_e32 v193, 0x3f4c422a, v193
	v_mul_f32_e32 v190, 0xc038aa3b, v190
	v_mul_f32_e32 v191, 0xc038aa3b, v191
	v_mul_f32_e32 v192, 0xc038aa3b, v192
	v_mul_f32_e32 v193, 0xc038aa3b, v193
	v_exp_f32_e32 v190, v190
	v_exp_f32_e32 v191, v191
	v_exp_f32_e32 v192, v192
	v_exp_f32_e32 v193, v193
	v_add_f32_e32 v190, 1.0, v190
	v_add_f32_e32 v191, 1.0, v191
	v_add_f32_e32 v192, 1.0, v192
	v_add_f32_e32 v193, 1.0, v193
	v_rcp_f32_e32 v190, v190
	v_rcp_f32_e32 v191, v191
	v_rcp_f32_e32 v192, v192
	v_rcp_f32_e32 v193, v193
	v_mul_f32_e32 v194, v194, v190
	v_mul_f32_e32 v195, v195, v191
	v_mul_f32_e32 v196, v196, v192
	v_mul_f32_e32 v197, v197, v193
	v_cvt_pk_bf16_f32 v194, v194, v195
	v_cvt_pk_bf16_f32 v195, v196, v197
	global_store_dwordx2 v[102:103], v[194:195], off offset:16
	s_waitcnt vmcnt(15)
	v_lshlrev_b32_e32 v182, 16, v170
	v_and_b32_e32 v183, 0xffff0000, v170
	v_lshlrev_b32_e32 v184, 16, v171
	v_and_b32_e32 v185, 0xffff0000, v171
	v_fma_f32 v194, v174, v182, v10
	v_fma_f32 v195, v175, v183, v11
	v_fma_f32 v196, v176, v184, v12
	v_fma_f32 v197, v177, v185, v13
	v_mul_f32_e32 v190, 0x3d372713, v194
	v_mul_f32_e32 v191, 0x3d372713, v195
	v_mul_f32_e32 v192, 0x3d372713, v196
	v_mul_f32_e32 v193, 0x3d372713, v197
	v_mul_f32_e32 v190, v194, v190
	v_mul_f32_e32 v191, v195, v191
	v_mul_f32_e32 v192, v196, v192
	v_mul_f32_e32 v193, v197, v193
	v_fma_f32 v190, v194, v190, v194
	v_fma_f32 v191, v195, v191, v195
	v_fma_f32 v192, v196, v192, v196
	v_fma_f32 v193, v197, v193, v197
	v_mul_f32_e32 v190, 0x3f4c422a, v190
	v_mul_f32_e32 v191, 0x3f4c422a, v191
	v_mul_f32_e32 v192, 0x3f4c422a, v192
	v_mul_f32_e32 v193, 0x3f4c422a, v193
	v_mul_f32_e32 v190, 0xc038aa3b, v190
	v_mul_f32_e32 v191, 0xc038aa3b, v191
	v_mul_f32_e32 v192, 0xc038aa3b, v192
	v_mul_f32_e32 v193, 0xc038aa3b, v193
	v_exp_f32_e32 v190, v190
	v_exp_f32_e32 v191, v191
	v_exp_f32_e32 v192, v192
	v_exp_f32_e32 v193, v193
	v_add_f32_e32 v190, 1.0, v190
	v_add_f32_e32 v191, 1.0, v191
	v_add_f32_e32 v192, 1.0, v192
	v_add_f32_e32 v193, 1.0, v193
	v_rcp_f32_e32 v190, v190
	v_rcp_f32_e32 v191, v191
	v_rcp_f32_e32 v192, v192
	v_rcp_f32_e32 v193, v193
	v_mul_f32_e32 v194, v194, v190
	v_mul_f32_e32 v195, v195, v191
	v_mul_f32_e32 v196, v196, v192
	v_mul_f32_e32 v197, v197, v193
	v_cvt_pk_bf16_f32 v194, v194, v195
	v_cvt_pk_bf16_f32 v195, v196, v197
	global_store_dwordx2 v[102:103], v[194:195], off offset:1024
	s_waitcnt vmcnt(15)
	v_lshlrev_b32_e32 v182, 16, v172
	v_and_b32_e32 v183, 0xffff0000, v172
	v_lshlrev_b32_e32 v184, 16, v173
	v_and_b32_e32 v185, 0xffff0000, v173
	v_fma_f32 v194, v178, v182, v14
	v_fma_f32 v195, v179, v183, v15
	v_fma_f32 v196, v180, v184, v16
	v_fma_f32 v197, v181, v185, v17
	v_mul_f32_e32 v190, 0x3d372713, v194
	v_mul_f32_e32 v191, 0x3d372713, v195
	v_mul_f32_e32 v192, 0x3d372713, v196
	v_mul_f32_e32 v193, 0x3d372713, v197
	v_mul_f32_e32 v190, v194, v190
	v_mul_f32_e32 v191, v195, v191
	v_mul_f32_e32 v192, v196, v192
	v_mul_f32_e32 v193, v197, v193
	v_fma_f32 v190, v194, v190, v194
	v_fma_f32 v191, v195, v191, v195
	v_fma_f32 v192, v196, v192, v196
	v_fma_f32 v193, v197, v193, v197
	v_mul_f32_e32 v190, 0x3f4c422a, v190
	v_mul_f32_e32 v191, 0x3f4c422a, v191
	v_mul_f32_e32 v192, 0x3f4c422a, v192
	v_mul_f32_e32 v193, 0x3f4c422a, v193
	v_mul_f32_e32 v190, 0xc038aa3b, v190
	v_mul_f32_e32 v191, 0xc038aa3b, v191
	v_mul_f32_e32 v192, 0xc038aa3b, v192
	v_mul_f32_e32 v193, 0xc038aa3b, v193
	v_exp_f32_e32 v190, v190
	v_exp_f32_e32 v191, v191
	v_exp_f32_e32 v192, v192
	v_exp_f32_e32 v193, v193
	v_add_f32_e32 v190, 1.0, v190
	v_add_f32_e32 v191, 1.0, v191
	v_add_f32_e32 v192, 1.0, v192
	v_add_f32_e32 v193, 1.0, v193
	v_rcp_f32_e32 v190, v190
	v_rcp_f32_e32 v191, v191
	v_rcp_f32_e32 v192, v192
	v_rcp_f32_e32 v193, v193
	v_mul_f32_e32 v194, v194, v190
	v_mul_f32_e32 v195, v195, v191
	v_mul_f32_e32 v196, v196, v192
	v_mul_f32_e32 v197, v197, v193
	v_cvt_pk_bf16_f32 v194, v194, v195
	v_cvt_pk_bf16_f32 v195, v196, v197
	global_store_dwordx2 v[102:103], v[194:195], off offset:1040
	s_branch .LBB0_963
